# s_setprio 1 moved ahead of the s_barrier that opens each of the 36 GEMM compute segments (one instruction off the post-release path), on keep_v8
# speedup vs baseline: 1.0067x; 1.0067x over previous
.LBB0_182:
	s_add_u32 s6, s4, 0xfffc0080
	s_addc_u32 s7, s5, -1
	s_add_i32 s9, 0, 0x10000
	s_cmp_eq_u32 s53, 12
	s_cselect_b32 s27, s39, s7
	s_cselect_b32 s26, s49, s6
	v_add_u32_e32 v0, s9, v189
	s_cselect_b32 s7, s15, s52
	s_cselect_b32 s6, s50, s51
	s_add_i32 s83, 0, 0x14000
	ds_read_b128 v[130:133], v0
	ds_read_b128 v[134:137], v0 offset:1024
	ds_read_b128 v[162:165], v0 offset:2048
	ds_read_b128 v[166:169], v0 offset:3072
	v_add_u32_e32 v0, s83, v189
	ds_read_b128 v[170:173], v0
	ds_read_b128 v[174:177], v0 offset:1024
	ds_read_b128 v[178:181], v0 offset:2048
	ds_read_b128 v[182:185], v0 offset:3072
	v_lshl_add_u64 v[148:149], s[4:5], 0, v[158:159]
	s_add_i32 m0, s40, 0xc000
	ds_read_b128 v[196:199], v193
	ds_read_b128 v[200:203], v193 offset:1024
	ds_read_b128 v[204:207], v193 offset:2048
	ds_read_b128 v[208:211], v193 offset:3072
	ds_read_b128 v[212:215], v193 offset:4096
	ds_read_b128 v[216:219], v193 offset:5120
	ds_read_b128 v[220:223], v193 offset:6144
	ds_read_b128 v[224:227], v193 offset:7168
	global_load_lds_dwordx4 v[148:149], off
	s_add_i32 m0, s40, 0xe000
	v_lshl_add_u64 v[148:149], s[4:5], 0, v[160:161]
	global_load_lds_dwordx4 v[148:149], off
	s_waitcnt vmcnt(8)
	s_waitcnt lgkmcnt(0)
	s_setprio 1
	s_barrier
	v_mfma_f32_16x16x32_bf16 v[126:129], v[130:133], v[196:199], v[126:129]
	v_mfma_f32_16x16x32_bf16 v[122:125], v[162:165], v[196:199], v[122:125]
	v_mfma_f32_16x16x32_bf16 v[118:121], v[130:133], v[204:207], v[118:121]
	v_mfma_f32_16x16x32_bf16 v[114:117], v[162:165], v[204:207], v[114:117]
	v_mfma_f32_16x16x32_bf16 v[102:105], v[130:133], v[212:215], v[102:105]
	v_mfma_f32_16x16x32_bf16 v[98:101], v[162:165], v[212:215], v[98:101]
	v_mfma_f32_16x16x32_bf16 v[86:89], v[130:133], v[220:223], v[86:89]
	v_mfma_f32_16x16x32_bf16 v[82:85], v[162:165], v[220:223], v[82:85]
	v_mfma_f32_16x16x32_bf16 v[126:129], v[134:137], v[200:203], v[126:129]
	v_mfma_f32_16x16x32_bf16 v[122:125], v[166:169], v[200:203], v[122:125]
	v_mfma_f32_16x16x32_bf16 v[118:121], v[134:137], v[208:211], v[118:121]
	v_mfma_f32_16x16x32_bf16 v[114:117], v[166:169], v[208:211], v[114:117]
	v_mfma_f32_16x16x32_bf16 v[102:105], v[134:137], v[216:219], v[102:105]
	v_mfma_f32_16x16x32_bf16 v[98:101], v[166:169], v[216:219], v[98:101]
	v_mfma_f32_16x16x32_bf16 v[86:89], v[134:137], v[224:227], v[86:89]
	v_mfma_f32_16x16x32_bf16 v[82:85], v[166:169], v[224:227], v[82:85]
	v_mfma_f32_16x16x32_bf16 v[110:113], v[170:173], v[196:199], v[110:113]
	v_mfma_f32_16x16x32_bf16 v[106:109], v[178:181], v[196:199], v[106:109]
	v_mfma_f32_16x16x32_bf16 v[94:97], v[170:173], v[204:207], v[94:97]
	v_mfma_f32_16x16x32_bf16 v[90:93], v[178:181], v[204:207], v[90:93]
	v_mfma_f32_16x16x32_bf16 v[78:81], v[170:173], v[212:215], v[78:81]
	v_mfma_f32_16x16x32_bf16 v[74:77], v[178:181], v[212:215], v[74:77]
	v_mfma_f32_16x16x32_bf16 v[70:73], v[170:173], v[220:223], v[70:73]
	v_mfma_f32_16x16x32_bf16 v[66:69], v[178:181], v[220:223], v[66:69]
	v_mfma_f32_16x16x32_bf16 v[110:113], v[174:177], v[200:203], v[110:113]
	v_mfma_f32_16x16x32_bf16 v[106:109], v[182:185], v[200:203], v[106:109]
	v_mfma_f32_16x16x32_bf16 v[94:97], v[174:177], v[208:211], v[94:97]
	v_mfma_f32_16x16x32_bf16 v[90:93], v[182:185], v[208:211], v[90:93]
	v_mfma_f32_16x16x32_bf16 v[78:81], v[174:177], v[216:219], v[78:81]
	v_mfma_f32_16x16x32_bf16 v[74:77], v[182:185], v[216:219], v[74:77]
	v_mfma_f32_16x16x32_bf16 v[70:73], v[174:177], v[224:227], v[70:73]
	v_mfma_f32_16x16x32_bf16 v[66:69], v[182:185], v[224:227], v[66:69]
	s_setprio 0
	s_barrier
	s_add_i32 s9, s9, s29
	v_lshl_add_u64 v[148:149], s[6:7], 0, v[142:143]
	s_mov_b32 m0, s9
	ds_read_b128 v[196:199], v193 offset:16384
	ds_read_b128 v[200:203], v193 offset:17408
	ds_read_b128 v[204:207], v193 offset:18432
	ds_read_b128 v[208:211], v193 offset:19456
	ds_read_b128 v[212:215], v193 offset:20480
	ds_read_b128 v[216:219], v193 offset:21504
	ds_read_b128 v[220:223], v193 offset:22528
	ds_read_b128 v[224:227], v193 offset:23552
	global_load_lds_dwordx4 v[148:149], off
	s_add_i32 m0, s9, 0x2000
	s_add_u32 s78, s6, 0x40000
	v_lshl_add_u64 v[150:151], s[6:7], 0, v[138:139]
	s_addc_u32 s79, s7, 0
	s_add_i32 s9, s83, s29
	global_load_lds_dwordx4 v[150:151], off
	v_lshl_add_u64 v[186:187], s[78:79], 0, v[142:143]
	s_mov_b32 m0, s9
	v_lshl_add_u64 v[228:229], s[26:27], 0, v[140:141]
	global_load_lds_dwordx4 v[186:187], off
	s_add_i32 m0, s9, 0x2000
	v_lshl_add_u64 v[186:187], s[78:79], 0, v[138:139]
	global_load_lds_dwordx4 v[186:187], off
	s_mov_b32 m0, s40
	v_lshl_add_u64 v[186:187], s[26:27], 0, v[144:145]
	global_load_lds_dwordx4 v[186:187], off
	s_mov_b32 m0, s41
	s_nop 0
	global_load_lds_dwordx4 v[228:229], off
	s_waitcnt vmcnt(8)
	s_waitcnt lgkmcnt(0)
	s_setprio 1
	s_barrier
	v_mfma_f32_16x16x32_bf16 v[62:65], v[130:133], v[196:199], v[62:65]
	v_mfma_f32_16x16x32_bf16 v[58:61], v[162:165], v[196:199], v[58:61]
	v_mfma_f32_16x16x32_bf16 v[54:57], v[130:133], v[204:207], v[54:57]
	v_mfma_f32_16x16x32_bf16 v[50:53], v[162:165], v[204:207], v[50:53]
	v_mfma_f32_16x16x32_bf16 v[38:41], v[130:133], v[212:215], v[38:41]
	v_mfma_f32_16x16x32_bf16 v[34:37], v[162:165], v[212:215], v[34:37]
	v_mfma_f32_16x16x32_bf16 v[22:25], v[130:133], v[220:223], v[22:25]
	v_mfma_f32_16x16x32_bf16 v[18:21], v[162:165], v[220:223], v[18:21]
	v_mfma_f32_16x16x32_bf16 v[62:65], v[134:137], v[200:203], v[62:65]
	v_mfma_f32_16x16x32_bf16 v[58:61], v[166:169], v[200:203], v[58:61]
	v_mfma_f32_16x16x32_bf16 v[54:57], v[134:137], v[208:211], v[54:57]
	v_mfma_f32_16x16x32_bf16 v[50:53], v[166:169], v[208:211], v[50:53]
	v_mfma_f32_16x16x32_bf16 v[38:41], v[134:137], v[216:219], v[38:41]
	v_mfma_f32_16x16x32_bf16 v[34:37], v[166:169], v[216:219], v[34:37]
	v_mfma_f32_16x16x32_bf16 v[22:25], v[134:137], v[224:227], v[22:25]
	v_mfma_f32_16x16x32_bf16 v[18:21], v[166:169], v[224:227], v[18:21]
	v_mfma_f32_16x16x32_bf16 v[46:49], v[170:173], v[196:199], v[46:49]
	v_mfma_f32_16x16x32_bf16 v[42:45], v[178:181], v[196:199], v[42:45]
	v_mfma_f32_16x16x32_bf16 v[30:33], v[170:173], v[204:207], v[30:33]
	v_mfma_f32_16x16x32_bf16 v[26:29], v[178:181], v[204:207], v[26:29]
	v_mfma_f32_16x16x32_bf16 v[14:17], v[170:173], v[212:215], v[14:17]
	v_mfma_f32_16x16x32_bf16 v[10:13], v[178:181], v[212:215], v[10:13]
	v_mfma_f32_16x16x32_bf16 v[6:9], v[170:173], v[220:223], v[6:9]
	v_mfma_f32_16x16x32_bf16 v[2:5], v[178:181], v[220:223], v[2:5]
	v_mfma_f32_16x16x32_bf16 v[46:49], v[174:177], v[200:203], v[46:49]
	v_mfma_f32_16x16x32_bf16 v[42:45], v[182:185], v[200:203], v[42:45]
	v_mfma_f32_16x16x32_bf16 v[30:33], v[174:177], v[208:211], v[30:33]
	v_mfma_f32_16x16x32_bf16 v[26:29], v[182:185], v[208:211], v[26:29]
	v_mfma_f32_16x16x32_bf16 v[14:17], v[174:177], v[216:219], v[14:17]
	v_mfma_f32_16x16x32_bf16 v[10:13], v[182:185], v[216:219], v[10:13]
	v_mfma_f32_16x16x32_bf16 v[6:9], v[174:177], v[224:227], v[6:9]
	v_mfma_f32_16x16x32_bf16 v[2:5], v[182:185], v[224:227], v[2:5]
	s_setprio 0
	s_barrier
	s_add_i32 s9, 0, 0x18000
	v_add_u32_e32 v0, s9, v189
	s_add_i32 s78, 0, 0x1c000
	ds_read_b128 v[130:133], v0
	ds_read_b128 v[134:137], v0 offset:1024
	ds_read_b128 v[162:165], v0 offset:2048
	ds_read_b128 v[166:169], v0 offset:3072
	v_add_u32_e32 v0, s78, v189
	ds_read_b128 v[170:173], v0
	ds_read_b128 v[174:177], v0 offset:1024
	ds_read_b128 v[178:181], v0 offset:2048
	ds_read_b128 v[182:185], v0 offset:3072
	s_add_u32 s26, s26, 0x40000
	s_addc_u32 s27, s27, 0
	s_mov_b32 m0, s42
	v_lshl_add_u64 v[230:231], s[26:27], 0, v[144:145]
	ds_read_b128 v[196:199], v193 offset:32768
	ds_read_b128 v[200:203], v193 offset:33792
	ds_read_b128 v[204:207], v193 offset:34816
	ds_read_b128 v[208:211], v193 offset:35840
	ds_read_b128 v[212:215], v193 offset:36864
	ds_read_b128 v[216:219], v193 offset:37888
	ds_read_b128 v[220:223], v193 offset:38912
	ds_read_b128 v[224:227], v193 offset:39936
	global_load_lds_dwordx4 v[230:231], off
	s_mov_b32 m0, s43
	v_lshl_add_u64 v[230:231], s[26:27], 0, v[140:141]
	global_load_lds_dwordx4 v[230:231], off
	s_waitcnt vmcnt(8)
	s_waitcnt lgkmcnt(0)
	s_setprio 1
	s_barrier
	v_mfma_f32_16x16x32_bf16 v[126:129], v[130:133], v[196:199], v[126:129]
	v_mfma_f32_16x16x32_bf16 v[122:125], v[162:165], v[196:199], v[122:125]
	v_mfma_f32_16x16x32_bf16 v[118:121], v[130:133], v[204:207], v[118:121]
	v_mfma_f32_16x16x32_bf16 v[114:117], v[162:165], v[204:207], v[114:117]
	v_mfma_f32_16x16x32_bf16 v[102:105], v[130:133], v[212:215], v[102:105]
	v_mfma_f32_16x16x32_bf16 v[98:101], v[162:165], v[212:215], v[98:101]
	v_mfma_f32_16x16x32_bf16 v[86:89], v[130:133], v[220:223], v[86:89]
	v_mfma_f32_16x16x32_bf16 v[82:85], v[162:165], v[220:223], v[82:85]
	v_mfma_f32_16x16x32_bf16 v[126:129], v[134:137], v[200:203], v[126:129]
	v_mfma_f32_16x16x32_bf16 v[122:125], v[166:169], v[200:203], v[122:125]
	v_mfma_f32_16x16x32_bf16 v[118:121], v[134:137], v[208:211], v[118:121]
	v_mfma_f32_16x16x32_bf16 v[114:117], v[166:169], v[208:211], v[114:117]
	v_mfma_f32_16x16x32_bf16 v[102:105], v[134:137], v[216:219], v[102:105]
	v_mfma_f32_16x16x32_bf16 v[98:101], v[166:169], v[216:219], v[98:101]
	v_mfma_f32_16x16x32_bf16 v[86:89], v[134:137], v[224:227], v[86:89]
	v_mfma_f32_16x16x32_bf16 v[82:85], v[166:169], v[224:227], v[82:85]
	v_mfma_f32_16x16x32_bf16 v[110:113], v[170:173], v[196:199], v[110:113]
	v_mfma_f32_16x16x32_bf16 v[106:109], v[178:181], v[196:199], v[106:109]
	v_mfma_f32_16x16x32_bf16 v[94:97], v[170:173], v[204:207], v[94:97]
	v_mfma_f32_16x16x32_bf16 v[90:93], v[178:181], v[204:207], v[90:93]
	v_mfma_f32_16x16x32_bf16 v[78:81], v[170:173], v[212:215], v[78:81]
	v_mfma_f32_16x16x32_bf16 v[74:77], v[178:181], v[212:215], v[74:77]
	v_mfma_f32_16x16x32_bf16 v[70:73], v[170:173], v[220:223], v[70:73]
	v_mfma_f32_16x16x32_bf16 v[66:69], v[178:181], v[220:223], v[66:69]
	v_mfma_f32_16x16x32_bf16 v[110:113], v[174:177], v[200:203], v[110:113]
	v_mfma_f32_16x16x32_bf16 v[106:109], v[182:185], v[200:203], v[106:109]
	v_mfma_f32_16x16x32_bf16 v[94:97], v[174:177], v[208:211], v[94:97]
	v_mfma_f32_16x16x32_bf16 v[90:93], v[182:185], v[208:211], v[90:93]
	v_mfma_f32_16x16x32_bf16 v[78:81], v[174:177], v[216:219], v[78:81]
	v_mfma_f32_16x16x32_bf16 v[74:77], v[182:185], v[216:219], v[74:77]
	v_mfma_f32_16x16x32_bf16 v[70:73], v[174:177], v[224:227], v[70:73]
	v_mfma_f32_16x16x32_bf16 v[66:69], v[182:185], v[224:227], v[66:69]
	s_setprio 0
	s_barrier
	s_add_i32 s9, s9, s29
	v_lshl_add_u64 v[148:149], v[148:149], 0, s[70:71]
	s_mov_b32 m0, s9
	ds_read_b128 v[196:199], v193 offset:49152
	ds_read_b128 v[200:203], v193 offset:50176
	ds_read_b128 v[204:207], v193 offset:51200
	ds_read_b128 v[208:211], v193 offset:52224
	ds_read_b128 v[212:215], v193 offset:53248
	ds_read_b128 v[216:219], v193 offset:54272
	ds_read_b128 v[220:223], v193 offset:55296
	ds_read_b128 v[224:227], v193 offset:56320
	global_load_lds_dwordx4 v[148:149], off
	s_add_i32 m0, s9, 0x2000
	s_add_u32 s6, s6, 0x40080
	v_lshl_add_u64 v[148:149], v[150:151], 0, s[70:71]
	s_addc_u32 s7, s7, 0
	s_add_i32 s9, s78, s29
	global_load_lds_dwordx4 v[148:149], off
	s_mov_b32 m0, s9
	v_lshl_add_u64 v[148:149], s[6:7], 0, v[142:143]
	global_load_lds_dwordx4 v[148:149], off
	s_add_i32 m0, s9, 0x2000
	v_lshl_add_u64 v[148:149], s[6:7], 0, v[138:139]
	global_load_lds_dwordx4 v[148:149], off
	s_mov_b32 m0, s44
	v_lshl_add_u64 v[148:149], v[186:187], 0, s[70:71]
	global_load_lds_dwordx4 v[148:149], off
	s_mov_b32 m0, s45
	v_lshl_add_u64 v[148:149], v[228:229], 0, s[70:71]
	global_load_lds_dwordx4 v[148:149], off
	s_waitcnt vmcnt(8)
	s_waitcnt lgkmcnt(0)
	s_setprio 1
	s_barrier
	v_mfma_f32_16x16x32_bf16 v[62:65], v[130:133], v[196:199], v[62:65]
	v_mfma_f32_16x16x32_bf16 v[58:61], v[162:165], v[196:199], v[58:61]
	v_mfma_f32_16x16x32_bf16 v[54:57], v[130:133], v[204:207], v[54:57]
	v_mfma_f32_16x16x32_bf16 v[50:53], v[162:165], v[204:207], v[50:53]
	v_mfma_f32_16x16x32_bf16 v[38:41], v[130:133], v[212:215], v[38:41]
	v_mfma_f32_16x16x32_bf16 v[34:37], v[162:165], v[212:215], v[34:37]
	v_mfma_f32_16x16x32_bf16 v[22:25], v[130:133], v[220:223], v[22:25]
	v_mfma_f32_16x16x32_bf16 v[18:21], v[162:165], v[220:223], v[18:21]
	v_mfma_f32_16x16x32_bf16 v[62:65], v[134:137], v[200:203], v[62:65]
	v_mfma_f32_16x16x32_bf16 v[58:61], v[166:169], v[200:203], v[58:61]
	v_mfma_f32_16x16x32_bf16 v[54:57], v[134:137], v[208:211], v[54:57]
	v_mfma_f32_16x16x32_bf16 v[50:53], v[166:169], v[208:211], v[50:53]
	v_mfma_f32_16x16x32_bf16 v[38:41], v[134:137], v[216:219], v[38:41]
	v_mfma_f32_16x16x32_bf16 v[34:37], v[166:169], v[216:219], v[34:37]
	v_mfma_f32_16x16x32_bf16 v[22:25], v[134:137], v[224:227], v[22:25]
	v_mfma_f32_16x16x32_bf16 v[18:21], v[166:169], v[224:227], v[18:21]
	v_mfma_f32_16x16x32_bf16 v[46:49], v[170:173], v[196:199], v[46:49]
	v_mfma_f32_16x16x32_bf16 v[42:45], v[178:181], v[196:199], v[42:45]
	v_mfma_f32_16x16x32_bf16 v[30:33], v[170:173], v[204:207], v[30:33]
	v_mfma_f32_16x16x32_bf16 v[26:29], v[178:181], v[204:207], v[26:29]
	v_mfma_f32_16x16x32_bf16 v[14:17], v[170:173], v[212:215], v[14:17]
	v_mfma_f32_16x16x32_bf16 v[10:13], v[178:181], v[212:215], v[10:13]
	v_mfma_f32_16x16x32_bf16 v[6:9], v[170:173], v[220:223], v[6:9]
	v_mfma_f32_16x16x32_bf16 v[2:5], v[178:181], v[220:223], v[2:5]
	v_mfma_f32_16x16x32_bf16 v[46:49], v[174:177], v[200:203], v[46:49]
	v_mfma_f32_16x16x32_bf16 v[42:45], v[182:185], v[200:203], v[42:45]
	v_mfma_f32_16x16x32_bf16 v[30:33], v[174:177], v[208:211], v[30:33]
	v_mfma_f32_16x16x32_bf16 v[26:29], v[182:185], v[208:211], v[26:29]
	v_mfma_f32_16x16x32_bf16 v[14:17], v[174:177], v[216:219], v[14:17]
	v_mfma_f32_16x16x32_bf16 v[10:13], v[182:185], v[216:219], v[10:13]
	v_mfma_f32_16x16x32_bf16 v[6:9], v[174:177], v[224:227], v[6:9]
	v_mfma_f32_16x16x32_bf16 v[2:5], v[182:185], v[224:227], v[2:5]
	s_setprio 0
	s_barrier
	s_add_i32 s53, s53, 2
	s_add_u32 s4, s4, 0x100
	s_addc_u32 s5, s5, 0
	s_add_u32 s51, s51, 0x100
	s_addc_u32 s52, s52, 0
	s_cmp_gt_u32 s53, 13
	s_cbranch_scc0 .LBB0_182
	s_and_b64 vcc, exec, s[36:37]
	s_cbranch_vccz .LBB0_185
	s_barrier

.LBB0_220:
	s_add_u32 s9, s36, 0xfffc0080
	s_addc_u32 s26, s37, -1
	s_add_i32 s60, 0, 0x10000
	s_cmp_eq_u32 s53, 12
	s_cselect_b32 s39, s19, s26
	s_cselect_b32 s38, s49, s9
	v_add_u32_e32 v148, s60, v141
	s_cselect_b32 s27, s17, s52
	s_cselect_b32 s26, s50, s51
	s_add_i32 s9, 0, 0x14000
	ds_read_b128 v[144:147], v148
	ds_read_b128 v[156:159], v148 offset:1024
	ds_read_b128 v[160:163], v148 offset:2048
	ds_read_b128 v[164:167], v148 offset:3072
	v_add_u32_e32 v148, s9, v141
	ds_read_b128 v[168:171], v148
	ds_read_b128 v[172:175], v148 offset:1024
	ds_read_b128 v[176:179], v148 offset:2048
	ds_read_b128 v[180:183], v148 offset:3072
	v_lshl_add_u64 v[148:149], s[36:37], 0, v[136:137]
	s_add_i32 m0, s40, 0xc000
	ds_read_b128 v[184:187], v143
	ds_read_b128 v[188:191], v143 offset:1024
	ds_read_b128 v[192:195], v143 offset:2048
	ds_read_b128 v[196:199], v143 offset:3072
	ds_read_b128 v[200:203], v143 offset:4096
	ds_read_b128 v[204:207], v143 offset:5120
	ds_read_b128 v[208:211], v143 offset:6144
	ds_read_b128 v[212:215], v143 offset:7168
	global_load_lds_dwordx4 v[148:149], off
	s_add_i32 m0, s40, 0xe000
	v_lshl_add_u64 v[148:149], s[36:37], 0, v[138:139]
	global_load_lds_dwordx4 v[148:149], off
	s_waitcnt vmcnt(8)
	s_waitcnt lgkmcnt(0)
	s_setprio 1
	s_barrier
	v_mfma_f32_16x16x32_bf16 v[126:129], v[144:147], v[184:187], v[126:129]
	v_mfma_f32_16x16x32_bf16 v[122:125], v[160:163], v[184:187], v[122:125]
	v_mfma_f32_16x16x32_bf16 v[118:121], v[144:147], v[192:195], v[118:121]
	v_mfma_f32_16x16x32_bf16 v[114:117], v[160:163], v[192:195], v[114:117]
	v_mfma_f32_16x16x32_bf16 v[102:105], v[144:147], v[200:203], v[102:105]
	v_mfma_f32_16x16x32_bf16 v[98:101], v[160:163], v[200:203], v[98:101]
	v_mfma_f32_16x16x32_bf16 v[86:89], v[144:147], v[208:211], v[86:89]
	v_mfma_f32_16x16x32_bf16 v[82:85], v[160:163], v[208:211], v[82:85]
	v_mfma_f32_16x16x32_bf16 v[126:129], v[156:159], v[188:191], v[126:129]
	v_mfma_f32_16x16x32_bf16 v[122:125], v[164:167], v[188:191], v[122:125]
	v_mfma_f32_16x16x32_bf16 v[118:121], v[156:159], v[196:199], v[118:121]
	v_mfma_f32_16x16x32_bf16 v[114:117], v[164:167], v[196:199], v[114:117]
	v_mfma_f32_16x16x32_bf16 v[102:105], v[156:159], v[204:207], v[102:105]
	v_mfma_f32_16x16x32_bf16 v[98:101], v[164:167], v[204:207], v[98:101]
	v_mfma_f32_16x16x32_bf16 v[86:89], v[156:159], v[212:215], v[86:89]
	v_mfma_f32_16x16x32_bf16 v[82:85], v[164:167], v[212:215], v[82:85]
	v_mfma_f32_16x16x32_bf16 v[110:113], v[168:171], v[184:187], v[110:113]
	v_mfma_f32_16x16x32_bf16 v[106:109], v[176:179], v[184:187], v[106:109]
	v_mfma_f32_16x16x32_bf16 v[94:97], v[168:171], v[192:195], v[94:97]
	v_mfma_f32_16x16x32_bf16 v[90:93], v[176:179], v[192:195], v[90:93]
	v_mfma_f32_16x16x32_bf16 v[78:81], v[168:171], v[200:203], v[78:81]
	v_mfma_f32_16x16x32_bf16 v[74:77], v[176:179], v[200:203], v[74:77]
	v_mfma_f32_16x16x32_bf16 v[70:73], v[168:171], v[208:211], v[70:73]
	v_mfma_f32_16x16x32_bf16 v[66:69], v[176:179], v[208:211], v[66:69]
	v_mfma_f32_16x16x32_bf16 v[110:113], v[172:175], v[188:191], v[110:113]
	v_mfma_f32_16x16x32_bf16 v[106:109], v[180:183], v[188:191], v[106:109]
	v_mfma_f32_16x16x32_bf16 v[94:97], v[172:175], v[196:199], v[94:97]
	v_mfma_f32_16x16x32_bf16 v[90:93], v[180:183], v[196:199], v[90:93]
	v_mfma_f32_16x16x32_bf16 v[78:81], v[172:175], v[204:207], v[78:81]
	v_mfma_f32_16x16x32_bf16 v[74:77], v[180:183], v[204:207], v[74:77]
	v_mfma_f32_16x16x32_bf16 v[70:73], v[172:175], v[212:215], v[70:73]
	v_mfma_f32_16x16x32_bf16 v[66:69], v[180:183], v[212:215], v[66:69]
	s_setprio 0
	s_barrier
	s_add_i32 s60, s60, s29
	v_lshl_add_u64 v[148:149], s[26:27], 0, v[0:1]
	s_mov_b32 m0, s60
	ds_read_b128 v[184:187], v143 offset:16384
	ds_read_b128 v[188:191], v143 offset:17408
	ds_read_b128 v[192:195], v143 offset:18432
	ds_read_b128 v[196:199], v143 offset:19456
	ds_read_b128 v[200:203], v143 offset:20480
	ds_read_b128 v[204:207], v143 offset:21504
	ds_read_b128 v[208:211], v143 offset:22528
	ds_read_b128 v[212:215], v143 offset:23552
	global_load_lds_dwordx4 v[148:149], off
	s_add_i32 m0, s60, 0x2000
	s_add_u32 s60, s26, 0x40000
	v_lshl_add_u64 v[150:151], s[26:27], 0, v[130:131]
	s_addc_u32 s61, s27, 0
	s_add_i32 s9, s9, s29
	global_load_lds_dwordx4 v[150:151], off
	v_lshl_add_u64 v[216:217], s[60:61], 0, v[0:1]
	s_mov_b32 m0, s9
	v_lshl_add_u64 v[218:219], s[38:39], 0, v[132:133]
	global_load_lds_dwordx4 v[216:217], off
	s_add_i32 m0, s9, 0x2000
	v_lshl_add_u64 v[216:217], s[60:61], 0, v[130:131]
	global_load_lds_dwordx4 v[216:217], off
	s_mov_b32 m0, s40
	v_lshl_add_u64 v[216:217], s[38:39], 0, v[134:135]
	global_load_lds_dwordx4 v[216:217], off
	s_mov_b32 m0, s41
	s_nop 0
	global_load_lds_dwordx4 v[218:219], off
	s_waitcnt vmcnt(8)
	s_waitcnt lgkmcnt(0)
	s_setprio 1
	s_barrier
	v_mfma_f32_16x16x32_bf16 v[62:65], v[144:147], v[184:187], v[62:65]
	v_mfma_f32_16x16x32_bf16 v[58:61], v[160:163], v[184:187], v[58:61]
	v_mfma_f32_16x16x32_bf16 v[54:57], v[144:147], v[192:195], v[54:57]
	v_mfma_f32_16x16x32_bf16 v[50:53], v[160:163], v[192:195], v[50:53]
	v_mfma_f32_16x16x32_bf16 v[38:41], v[144:147], v[200:203], v[38:41]
	v_mfma_f32_16x16x32_bf16 v[34:37], v[160:163], v[200:203], v[34:37]
	v_mfma_f32_16x16x32_bf16 v[22:25], v[144:147], v[208:211], v[22:25]
	v_mfma_f32_16x16x32_bf16 v[18:21], v[160:163], v[208:211], v[18:21]
	v_mfma_f32_16x16x32_bf16 v[62:65], v[156:159], v[188:191], v[62:65]
	v_mfma_f32_16x16x32_bf16 v[58:61], v[164:167], v[188:191], v[58:61]
	v_mfma_f32_16x16x32_bf16 v[54:57], v[156:159], v[196:199], v[54:57]
	v_mfma_f32_16x16x32_bf16 v[50:53], v[164:167], v[196:199], v[50:53]
	v_mfma_f32_16x16x32_bf16 v[38:41], v[156:159], v[204:207], v[38:41]
	v_mfma_f32_16x16x32_bf16 v[34:37], v[164:167], v[204:207], v[34:37]
	v_mfma_f32_16x16x32_bf16 v[22:25], v[156:159], v[212:215], v[22:25]
	v_mfma_f32_16x16x32_bf16 v[18:21], v[164:167], v[212:215], v[18:21]
	v_mfma_f32_16x16x32_bf16 v[46:49], v[168:171], v[184:187], v[46:49]
	v_mfma_f32_16x16x32_bf16 v[42:45], v[176:179], v[184:187], v[42:45]
	v_mfma_f32_16x16x32_bf16 v[30:33], v[168:171], v[192:195], v[30:33]
	v_mfma_f32_16x16x32_bf16 v[26:29], v[176:179], v[192:195], v[26:29]
	v_mfma_f32_16x16x32_bf16 v[14:17], v[168:171], v[200:203], v[14:17]
	v_mfma_f32_16x16x32_bf16 v[10:13], v[176:179], v[200:203], v[10:13]
	v_mfma_f32_16x16x32_bf16 v[6:9], v[168:171], v[208:211], v[6:9]
	v_mfma_f32_16x16x32_bf16 v[2:5], v[176:179], v[208:211], v[2:5]
	v_mfma_f32_16x16x32_bf16 v[46:49], v[172:175], v[188:191], v[46:49]
	v_mfma_f32_16x16x32_bf16 v[42:45], v[180:183], v[188:191], v[42:45]
	v_mfma_f32_16x16x32_bf16 v[30:33], v[172:175], v[196:199], v[30:33]
	v_mfma_f32_16x16x32_bf16 v[26:29], v[180:183], v[196:199], v[26:29]
	v_mfma_f32_16x16x32_bf16 v[14:17], v[172:175], v[204:207], v[14:17]
	v_mfma_f32_16x16x32_bf16 v[10:13], v[180:183], v[204:207], v[10:13]
	v_mfma_f32_16x16x32_bf16 v[6:9], v[172:175], v[212:215], v[6:9]
	v_mfma_f32_16x16x32_bf16 v[2:5], v[180:183], v[212:215], v[2:5]
	s_setprio 0
	s_barrier
	s_add_i32 s9, 0, 0x18000
	s_add_i32 s60, 0, 0x1c000
	v_add_u32_e32 v164, s9, v141
	v_add_u32_e32 v180, s60, v141
	ds_read_b128 v[144:147], v164
	ds_read_b128 v[156:159], v164 offset:1024
	ds_read_b128 v[160:163], v164 offset:2048
	ds_read_b128 v[164:167], v164 offset:3072
	ds_read_b128 v[168:171], v180
	ds_read_b128 v[172:175], v180 offset:1024
	ds_read_b128 v[176:179], v180 offset:2048
	ds_read_b128 v[180:183], v180 offset:3072
	s_add_u32 s38, s38, 0x40000
	s_addc_u32 s39, s39, 0
	s_mov_b32 m0, s42
	v_lshl_add_u64 v[220:221], s[38:39], 0, v[134:135]
	ds_read_b128 v[184:187], v143 offset:32768
	ds_read_b128 v[188:191], v143 offset:33792
	ds_read_b128 v[192:195], v143 offset:34816
	ds_read_b128 v[196:199], v143 offset:35840
	ds_read_b128 v[200:203], v143 offset:36864
	ds_read_b128 v[204:207], v143 offset:37888
	ds_read_b128 v[208:211], v143 offset:38912
	ds_read_b128 v[212:215], v143 offset:39936
	global_load_lds_dwordx4 v[220:221], off
	s_mov_b32 m0, s43
	v_lshl_add_u64 v[220:221], s[38:39], 0, v[132:133]
	global_load_lds_dwordx4 v[220:221], off
	s_waitcnt vmcnt(8)
	s_waitcnt lgkmcnt(0)
	s_setprio 1
	s_barrier
	v_mfma_f32_16x16x32_bf16 v[126:129], v[144:147], v[184:187], v[126:129]
	v_mfma_f32_16x16x32_bf16 v[122:125], v[160:163], v[184:187], v[122:125]
	v_mfma_f32_16x16x32_bf16 v[118:121], v[144:147], v[192:195], v[118:121]
	v_mfma_f32_16x16x32_bf16 v[114:117], v[160:163], v[192:195], v[114:117]
	v_mfma_f32_16x16x32_bf16 v[102:105], v[144:147], v[200:203], v[102:105]
	v_mfma_f32_16x16x32_bf16 v[98:101], v[160:163], v[200:203], v[98:101]
	v_mfma_f32_16x16x32_bf16 v[86:89], v[144:147], v[208:211], v[86:89]
	v_mfma_f32_16x16x32_bf16 v[82:85], v[160:163], v[208:211], v[82:85]
	v_mfma_f32_16x16x32_bf16 v[126:129], v[156:159], v[188:191], v[126:129]
	v_mfma_f32_16x16x32_bf16 v[122:125], v[164:167], v[188:191], v[122:125]
	v_mfma_f32_16x16x32_bf16 v[118:121], v[156:159], v[196:199], v[118:121]
	v_mfma_f32_16x16x32_bf16 v[114:117], v[164:167], v[196:199], v[114:117]
	v_mfma_f32_16x16x32_bf16 v[102:105], v[156:159], v[204:207], v[102:105]
	v_mfma_f32_16x16x32_bf16 v[98:101], v[164:167], v[204:207], v[98:101]
	v_mfma_f32_16x16x32_bf16 v[86:89], v[156:159], v[212:215], v[86:89]
	v_mfma_f32_16x16x32_bf16 v[82:85], v[164:167], v[212:215], v[82:85]
	v_mfma_f32_16x16x32_bf16 v[110:113], v[168:171], v[184:187], v[110:113]
	v_mfma_f32_16x16x32_bf16 v[106:109], v[176:179], v[184:187], v[106:109]
	v_mfma_f32_16x16x32_bf16 v[94:97], v[168:171], v[192:195], v[94:97]
	v_mfma_f32_16x16x32_bf16 v[90:93], v[176:179], v[192:195], v[90:93]
	v_mfma_f32_16x16x32_bf16 v[78:81], v[168:171], v[200:203], v[78:81]
	v_mfma_f32_16x16x32_bf16 v[74:77], v[176:179], v[200:203], v[74:77]
	v_mfma_f32_16x16x32_bf16 v[70:73], v[168:171], v[208:211], v[70:73]
	v_mfma_f32_16x16x32_bf16 v[66:69], v[176:179], v[208:211], v[66:69]
	v_mfma_f32_16x16x32_bf16 v[110:113], v[172:175], v[188:191], v[110:113]
	v_mfma_f32_16x16x32_bf16 v[106:109], v[180:183], v[188:191], v[106:109]
	v_mfma_f32_16x16x32_bf16 v[94:97], v[172:175], v[196:199], v[94:97]
	v_mfma_f32_16x16x32_bf16 v[90:93], v[180:183], v[196:199], v[90:93]
	v_mfma_f32_16x16x32_bf16 v[78:81], v[172:175], v[204:207], v[78:81]
	v_mfma_f32_16x16x32_bf16 v[74:77], v[180:183], v[204:207], v[74:77]
	v_mfma_f32_16x16x32_bf16 v[70:73], v[172:175], v[212:215], v[70:73]
	v_mfma_f32_16x16x32_bf16 v[66:69], v[180:183], v[212:215], v[66:69]
	s_setprio 0
	s_barrier
	s_add_i32 s9, s9, s29
	v_lshl_add_u64 v[148:149], v[148:149], 0, s[70:71]
	s_mov_b32 m0, s9
	ds_read_b128 v[184:187], v143 offset:49152
	ds_read_b128 v[188:191], v143 offset:50176
	ds_read_b128 v[192:195], v143 offset:51200
	ds_read_b128 v[196:199], v143 offset:52224
	ds_read_b128 v[200:203], v143 offset:53248
	ds_read_b128 v[204:207], v143 offset:54272
	ds_read_b128 v[208:211], v143 offset:55296
	ds_read_b128 v[212:215], v143 offset:56320
	global_load_lds_dwordx4 v[148:149], off
	s_add_i32 m0, s9, 0x2000
	s_add_u32 s26, s26, 0x40080
	v_lshl_add_u64 v[148:149], v[150:151], 0, s[70:71]
	s_addc_u32 s27, s27, 0
	s_add_i32 s9, s60, s29
	global_load_lds_dwordx4 v[148:149], off
	s_mov_b32 m0, s9
	v_lshl_add_u64 v[148:149], s[26:27], 0, v[0:1]
	global_load_lds_dwordx4 v[148:149], off
	s_add_i32 m0, s9, 0x2000
	v_lshl_add_u64 v[148:149], s[26:27], 0, v[130:131]
	global_load_lds_dwordx4 v[148:149], off
	s_mov_b32 m0, s44
	v_lshl_add_u64 v[148:149], v[216:217], 0, s[70:71]
	global_load_lds_dwordx4 v[148:149], off
	s_mov_b32 m0, s45
	v_lshl_add_u64 v[148:149], v[218:219], 0, s[70:71]
	global_load_lds_dwordx4 v[148:149], off
	s_waitcnt vmcnt(8)
	s_waitcnt lgkmcnt(0)
	s_setprio 1
	s_barrier
	v_mfma_f32_16x16x32_bf16 v[62:65], v[144:147], v[184:187], v[62:65]
	v_mfma_f32_16x16x32_bf16 v[58:61], v[160:163], v[184:187], v[58:61]
	v_mfma_f32_16x16x32_bf16 v[54:57], v[144:147], v[192:195], v[54:57]
	v_mfma_f32_16x16x32_bf16 v[50:53], v[160:163], v[192:195], v[50:53]
	v_mfma_f32_16x16x32_bf16 v[38:41], v[144:147], v[200:203], v[38:41]
	v_mfma_f32_16x16x32_bf16 v[34:37], v[160:163], v[200:203], v[34:37]
	v_mfma_f32_16x16x32_bf16 v[22:25], v[144:147], v[208:211], v[22:25]
	v_mfma_f32_16x16x32_bf16 v[18:21], v[160:163], v[208:211], v[18:21]
	v_mfma_f32_16x16x32_bf16 v[62:65], v[156:159], v[188:191], v[62:65]
	v_mfma_f32_16x16x32_bf16 v[58:61], v[164:167], v[188:191], v[58:61]
	v_mfma_f32_16x16x32_bf16 v[54:57], v[156:159], v[196:199], v[54:57]
	v_mfma_f32_16x16x32_bf16 v[50:53], v[164:167], v[196:199], v[50:53]
	v_mfma_f32_16x16x32_bf16 v[38:41], v[156:159], v[204:207], v[38:41]
	v_mfma_f32_16x16x32_bf16 v[34:37], v[164:167], v[204:207], v[34:37]
	v_mfma_f32_16x16x32_bf16 v[22:25], v[156:159], v[212:215], v[22:25]
	v_mfma_f32_16x16x32_bf16 v[18:21], v[164:167], v[212:215], v[18:21]
	v_mfma_f32_16x16x32_bf16 v[46:49], v[168:171], v[184:187], v[46:49]
	v_mfma_f32_16x16x32_bf16 v[42:45], v[176:179], v[184:187], v[42:45]
	v_mfma_f32_16x16x32_bf16 v[30:33], v[168:171], v[192:195], v[30:33]
	v_mfma_f32_16x16x32_bf16 v[26:29], v[176:179], v[192:195], v[26:29]
	v_mfma_f32_16x16x32_bf16 v[14:17], v[168:171], v[200:203], v[14:17]
	v_mfma_f32_16x16x32_bf16 v[10:13], v[176:179], v[200:203], v[10:13]
	v_mfma_f32_16x16x32_bf16 v[6:9], v[168:171], v[208:211], v[6:9]
	v_mfma_f32_16x16x32_bf16 v[2:5], v[176:179], v[208:211], v[2:5]
	v_mfma_f32_16x16x32_bf16 v[46:49], v[172:175], v[188:191], v[46:49]
	v_mfma_f32_16x16x32_bf16 v[42:45], v[180:183], v[188:191], v[42:45]
	v_mfma_f32_16x16x32_bf16 v[30:33], v[172:175], v[196:199], v[30:33]
	v_mfma_f32_16x16x32_bf16 v[26:29], v[180:183], v[196:199], v[26:29]
	v_mfma_f32_16x16x32_bf16 v[14:17], v[172:175], v[204:207], v[14:17]
	v_mfma_f32_16x16x32_bf16 v[10:13], v[180:183], v[204:207], v[10:13]
	v_mfma_f32_16x16x32_bf16 v[6:9], v[172:175], v[212:215], v[6:9]
	v_mfma_f32_16x16x32_bf16 v[2:5], v[180:183], v[212:215], v[2:5]
	s_setprio 0
	s_barrier
	s_add_i32 s53, s53, 2
	s_add_u32 s36, s36, 0x100
	s_addc_u32 s37, s37, 0
	s_add_u32 s51, s51, 0x100
	s_addc_u32 s52, s52, 0
	s_cmp_gt_u32 s53, 13
	s_cbranch_scc0 .LBB0_220
	s_and_b64 vcc, exec, s[14:15]
	s_cbranch_vccz .LBB0_223
	s_barrier

.LBB0_376:
	s_add_u32 s53, s18, s9
	s_addc_u32 s74, s19, 0
	s_add_u32 s60, s53, 0x100
	s_addc_u32 s61, s74, 0
	s_and_b64 s[26:27], s[38:39], exec
	s_cselect_b32 s61, s25, s61
	s_cselect_b32 s60, s24, s60
	s_add_u32 s9, s16, s9
	s_addc_u32 s26, s17, 0
	s_add_u32 s9, s9, 0x100
	s_addc_u32 s72, s26, 0
	s_add_i32 s92, 0, 0x10000
	s_and_b64 s[26:27], s[38:39], exec
	s_cselect_b32 s73, s23, s72
	s_cselect_b32 s72, s52, s9
	s_add_i32 s39, 0, 0x14000
	s_add_u32 vcc_lo, s53, 0x58080
	s_addc_u32 vcc_hi, s74, 0
	s_add_i32 s78, s92, s41
	s_add_i32 m0, s42, 0xc000
	s_add_i32 s93, s42, 0xe000
	s_add_i32 s91, s78, 0x2000
	v_add_u32_e32 v148, s92, v137
	s_add_u32 s74, s72, 0x10000
	ds_read_b128 v[140:143], v148
	ds_read_b128 v[144:147], v148 offset:1024
	ds_read_b128 v[156:159], v148 offset:2048
	ds_read_b128 v[160:163], v148 offset:3072
	v_add_u32_e32 v148, s39, v137
	s_addc_u32 s75, s73, 0
	s_add_i32 s79, s39, s41
	ds_read_b128 v[164:167], v148
	ds_read_b128 v[168:171], v148 offset:1024
	ds_read_b128 v[172:175], v148 offset:2048
	ds_read_b128 v[176:179], v148 offset:3072
	s_add_i32 s90, s79, 0x2000
	s_add_i32 s97, 0, 0x18000
	s_add_i32 s83, 0, 0x1c000
	s_add_u32 s26, s60, 0x58000
	s_addc_u32 s27, s61, 0
	s_add_i32 s53, s97, s41
	s_add_i32 s9, s53, 0x2000
	s_add_u32 s38, s72, 0x10080
	s_addc_u32 s39, s73, 0
	s_add_i32 s96, s83, s41
	s_add_i32 s92, s96, 0x2000
	v_lshl_add_u64 v[148:149], vcc, 0, v[134:135]
	ds_read_b128 v[180:183], v139
	ds_read_b128 v[184:187], v139 offset:1024
	ds_read_b128 v[188:191], v139 offset:2048
	ds_read_b128 v[192:195], v139 offset:3072
	ds_read_b128 v[196:199], v139 offset:4096
	ds_read_b128 v[200:203], v139 offset:5120
	ds_read_b128 v[204:207], v139 offset:6144
	ds_read_b128 v[208:211], v139 offset:7168
	global_load_lds_dwordx4 v[148:149], off
	s_mov_b32 m0, s93
	v_lshl_add_u64 v[148:149], vcc, 0, v[132:133]
	global_load_lds_dwordx4 v[148:149], off
	s_waitcnt vmcnt(8)
	s_waitcnt lgkmcnt(0)
	s_setprio 1
	s_barrier
	v_mfma_f32_16x16x32_bf16 v[126:129], v[140:143], v[180:183], v[126:129]
	v_mfma_f32_16x16x32_bf16 v[122:125], v[156:159], v[180:183], v[122:125]
	v_mfma_f32_16x16x32_bf16 v[118:121], v[140:143], v[188:191], v[118:121]
	v_mfma_f32_16x16x32_bf16 v[114:117], v[156:159], v[188:191], v[114:117]
	v_mfma_f32_16x16x32_bf16 v[102:105], v[140:143], v[196:199], v[102:105]
	v_mfma_f32_16x16x32_bf16 v[98:101], v[156:159], v[196:199], v[98:101]
	v_mfma_f32_16x16x32_bf16 v[86:89], v[140:143], v[204:207], v[86:89]
	v_mfma_f32_16x16x32_bf16 v[82:85], v[156:159], v[204:207], v[82:85]
	v_mfma_f32_16x16x32_bf16 v[126:129], v[144:147], v[184:187], v[126:129]
	v_mfma_f32_16x16x32_bf16 v[122:125], v[160:163], v[184:187], v[122:125]
	v_mfma_f32_16x16x32_bf16 v[118:121], v[144:147], v[192:195], v[118:121]
	v_mfma_f32_16x16x32_bf16 v[114:117], v[160:163], v[192:195], v[114:117]
	v_mfma_f32_16x16x32_bf16 v[102:105], v[144:147], v[200:203], v[102:105]
	v_mfma_f32_16x16x32_bf16 v[98:101], v[160:163], v[200:203], v[98:101]
	v_mfma_f32_16x16x32_bf16 v[86:89], v[144:147], v[208:211], v[86:89]
	v_mfma_f32_16x16x32_bf16 v[82:85], v[160:163], v[208:211], v[82:85]
	v_mfma_f32_16x16x32_bf16 v[110:113], v[164:167], v[180:183], v[110:113]
	v_mfma_f32_16x16x32_bf16 v[106:109], v[172:175], v[180:183], v[106:109]
	v_mfma_f32_16x16x32_bf16 v[94:97], v[164:167], v[188:191], v[94:97]
	v_mfma_f32_16x16x32_bf16 v[90:93], v[172:175], v[188:191], v[90:93]
	v_mfma_f32_16x16x32_bf16 v[78:81], v[164:167], v[196:199], v[78:81]
	v_mfma_f32_16x16x32_bf16 v[74:77], v[172:175], v[196:199], v[74:77]
	v_mfma_f32_16x16x32_bf16 v[70:73], v[164:167], v[204:207], v[70:73]
	v_mfma_f32_16x16x32_bf16 v[66:69], v[172:175], v[204:207], v[66:69]
	v_mfma_f32_16x16x32_bf16 v[110:113], v[168:171], v[184:187], v[110:113]
	v_mfma_f32_16x16x32_bf16 v[106:109], v[176:179], v[184:187], v[106:109]
	v_mfma_f32_16x16x32_bf16 v[94:97], v[168:171], v[192:195], v[94:97]
	v_mfma_f32_16x16x32_bf16 v[90:93], v[176:179], v[192:195], v[90:93]
	v_mfma_f32_16x16x32_bf16 v[78:81], v[168:171], v[200:203], v[78:81]
	v_mfma_f32_16x16x32_bf16 v[74:77], v[176:179], v[200:203], v[74:77]
	v_mfma_f32_16x16x32_bf16 v[70:73], v[168:171], v[208:211], v[70:73]
	v_mfma_f32_16x16x32_bf16 v[66:69], v[176:179], v[208:211], v[66:69]
	s_setprio 0
	s_barrier
	s_mov_b32 m0, s78
	v_lshl_add_u64 v[148:149], s[72:73], 0, v[0:1]
	ds_read_b128 v[180:183], v139 offset:16384
	ds_read_b128 v[184:187], v139 offset:17408
	ds_read_b128 v[188:191], v139 offset:18432
	ds_read_b128 v[192:195], v139 offset:19456
	ds_read_b128 v[196:199], v139 offset:20480
	ds_read_b128 v[200:203], v139 offset:21504
	ds_read_b128 v[204:207], v139 offset:22528
	ds_read_b128 v[208:211], v139 offset:23552
	global_load_lds_dwordx4 v[148:149], off
	v_lshl_add_u64 v[150:151], s[72:73], 0, v[130:131]
	s_mov_b32 m0, s91
	v_lshl_add_u64 v[212:213], s[74:75], 0, v[0:1]
	global_load_lds_dwordx4 v[150:151], off
	s_mov_b32 m0, s79
	v_lshl_add_u64 v[214:215], s[60:61], 0, v[132:133]
	global_load_lds_dwordx4 v[212:213], off
	s_mov_b32 m0, s90
	v_lshl_add_u64 v[212:213], s[74:75], 0, v[130:131]
	global_load_lds_dwordx4 v[212:213], off
	s_mov_b32 m0, s42
	v_lshl_add_u64 v[212:213], s[60:61], 0, v[134:135]
	global_load_lds_dwordx4 v[212:213], off
	s_mov_b32 m0, s43
	s_nop 0
	global_load_lds_dwordx4 v[214:215], off
	s_waitcnt vmcnt(8)
	s_waitcnt lgkmcnt(0)
	s_setprio 1
	s_barrier
	v_mfma_f32_16x16x32_bf16 v[62:65], v[140:143], v[180:183], v[62:65]
	v_mfma_f32_16x16x32_bf16 v[58:61], v[156:159], v[180:183], v[58:61]
	v_mfma_f32_16x16x32_bf16 v[54:57], v[140:143], v[188:191], v[54:57]
	v_mfma_f32_16x16x32_bf16 v[50:53], v[156:159], v[188:191], v[50:53]
	v_mfma_f32_16x16x32_bf16 v[38:41], v[140:143], v[196:199], v[38:41]
	v_mfma_f32_16x16x32_bf16 v[34:37], v[156:159], v[196:199], v[34:37]
	v_mfma_f32_16x16x32_bf16 v[22:25], v[140:143], v[204:207], v[22:25]
	v_mfma_f32_16x16x32_bf16 v[18:21], v[156:159], v[204:207], v[18:21]
	v_mfma_f32_16x16x32_bf16 v[62:65], v[144:147], v[184:187], v[62:65]
	v_mfma_f32_16x16x32_bf16 v[58:61], v[160:163], v[184:187], v[58:61]
	v_mfma_f32_16x16x32_bf16 v[54:57], v[144:147], v[192:195], v[54:57]
	v_mfma_f32_16x16x32_bf16 v[50:53], v[160:163], v[192:195], v[50:53]
	v_mfma_f32_16x16x32_bf16 v[38:41], v[144:147], v[200:203], v[38:41]
	v_mfma_f32_16x16x32_bf16 v[34:37], v[160:163], v[200:203], v[34:37]
	v_mfma_f32_16x16x32_bf16 v[22:25], v[144:147], v[208:211], v[22:25]
	v_mfma_f32_16x16x32_bf16 v[18:21], v[160:163], v[208:211], v[18:21]
	v_mfma_f32_16x16x32_bf16 v[46:49], v[164:167], v[180:183], v[46:49]
	v_mfma_f32_16x16x32_bf16 v[42:45], v[172:175], v[180:183], v[42:45]
	v_mfma_f32_16x16x32_bf16 v[30:33], v[164:167], v[188:191], v[30:33]
	v_mfma_f32_16x16x32_bf16 v[26:29], v[172:175], v[188:191], v[26:29]
	v_mfma_f32_16x16x32_bf16 v[14:17], v[164:167], v[196:199], v[14:17]
	v_mfma_f32_16x16x32_bf16 v[10:13], v[172:175], v[196:199], v[10:13]
	v_mfma_f32_16x16x32_bf16 v[6:9], v[164:167], v[204:207], v[6:9]
	v_mfma_f32_16x16x32_bf16 v[2:5], v[172:175], v[204:207], v[2:5]
	v_mfma_f32_16x16x32_bf16 v[46:49], v[168:171], v[184:187], v[46:49]
	v_mfma_f32_16x16x32_bf16 v[42:45], v[176:179], v[184:187], v[42:45]
	v_mfma_f32_16x16x32_bf16 v[30:33], v[168:171], v[192:195], v[30:33]
	v_mfma_f32_16x16x32_bf16 v[26:29], v[176:179], v[192:195], v[26:29]
	v_mfma_f32_16x16x32_bf16 v[14:17], v[168:171], v[200:203], v[14:17]
	v_mfma_f32_16x16x32_bf16 v[10:13], v[176:179], v[200:203], v[10:13]
	v_mfma_f32_16x16x32_bf16 v[6:9], v[168:171], v[208:211], v[6:9]
	v_mfma_f32_16x16x32_bf16 v[2:5], v[176:179], v[208:211], v[2:5]
	s_setprio 0
	s_barrier
	v_add_u32_e32 v160, s97, v137
	v_add_u32_e32 v176, s83, v137
	ds_read_b128 v[140:143], v160
	ds_read_b128 v[144:147], v160 offset:1024
	ds_read_b128 v[156:159], v160 offset:2048
	ds_read_b128 v[160:163], v160 offset:3072
	ds_read_b128 v[164:167], v176
	ds_read_b128 v[168:171], v176 offset:1024
	ds_read_b128 v[172:175], v176 offset:2048
	ds_read_b128 v[176:179], v176 offset:3072
	s_mov_b32 m0, s44
	v_lshl_add_u64 v[216:217], s[26:27], 0, v[134:135]
	ds_read_b128 v[180:183], v139 offset:32768
	ds_read_b128 v[184:187], v139 offset:33792
	ds_read_b128 v[188:191], v139 offset:34816
	ds_read_b128 v[192:195], v139 offset:35840
	ds_read_b128 v[196:199], v139 offset:36864
	ds_read_b128 v[200:203], v139 offset:37888
	ds_read_b128 v[204:207], v139 offset:38912
	ds_read_b128 v[208:211], v139 offset:39936
	global_load_lds_dwordx4 v[216:217], off
	s_mov_b32 m0, s45
	v_lshl_add_u64 v[216:217], s[26:27], 0, v[132:133]
	global_load_lds_dwordx4 v[216:217], off
	s_waitcnt vmcnt(8)
	s_waitcnt lgkmcnt(0)
	s_setprio 1
	s_barrier
	v_mfma_f32_16x16x32_bf16 v[126:129], v[140:143], v[180:183], v[126:129]
	v_mfma_f32_16x16x32_bf16 v[122:125], v[156:159], v[180:183], v[122:125]
	v_mfma_f32_16x16x32_bf16 v[118:121], v[140:143], v[188:191], v[118:121]
	v_mfma_f32_16x16x32_bf16 v[114:117], v[156:159], v[188:191], v[114:117]
	v_mfma_f32_16x16x32_bf16 v[102:105], v[140:143], v[196:199], v[102:105]
	v_mfma_f32_16x16x32_bf16 v[98:101], v[156:159], v[196:199], v[98:101]
	v_mfma_f32_16x16x32_bf16 v[86:89], v[140:143], v[204:207], v[86:89]
	v_mfma_f32_16x16x32_bf16 v[82:85], v[156:159], v[204:207], v[82:85]
	v_mfma_f32_16x16x32_bf16 v[126:129], v[144:147], v[184:187], v[126:129]
	v_mfma_f32_16x16x32_bf16 v[122:125], v[160:163], v[184:187], v[122:125]
	v_mfma_f32_16x16x32_bf16 v[118:121], v[144:147], v[192:195], v[118:121]
	v_mfma_f32_16x16x32_bf16 v[114:117], v[160:163], v[192:195], v[114:117]
	v_mfma_f32_16x16x32_bf16 v[102:105], v[144:147], v[200:203], v[102:105]
	v_mfma_f32_16x16x32_bf16 v[98:101], v[160:163], v[200:203], v[98:101]
	v_mfma_f32_16x16x32_bf16 v[86:89], v[144:147], v[208:211], v[86:89]
	v_mfma_f32_16x16x32_bf16 v[82:85], v[160:163], v[208:211], v[82:85]
	v_mfma_f32_16x16x32_bf16 v[110:113], v[164:167], v[180:183], v[110:113]
	v_mfma_f32_16x16x32_bf16 v[106:109], v[172:175], v[180:183], v[106:109]
	v_mfma_f32_16x16x32_bf16 v[94:97], v[164:167], v[188:191], v[94:97]
	v_mfma_f32_16x16x32_bf16 v[90:93], v[172:175], v[188:191], v[90:93]
	v_mfma_f32_16x16x32_bf16 v[78:81], v[164:167], v[196:199], v[78:81]
	v_mfma_f32_16x16x32_bf16 v[74:77], v[172:175], v[196:199], v[74:77]
	v_mfma_f32_16x16x32_bf16 v[70:73], v[164:167], v[204:207], v[70:73]
	v_mfma_f32_16x16x32_bf16 v[66:69], v[172:175], v[204:207], v[66:69]
	v_mfma_f32_16x16x32_bf16 v[110:113], v[168:171], v[184:187], v[110:113]
	v_mfma_f32_16x16x32_bf16 v[106:109], v[176:179], v[184:187], v[106:109]
	v_mfma_f32_16x16x32_bf16 v[94:97], v[168:171], v[192:195], v[94:97]
	v_mfma_f32_16x16x32_bf16 v[90:93], v[176:179], v[192:195], v[90:93]
	v_mfma_f32_16x16x32_bf16 v[78:81], v[168:171], v[200:203], v[78:81]
	v_mfma_f32_16x16x32_bf16 v[74:77], v[176:179], v[200:203], v[74:77]
	v_mfma_f32_16x16x32_bf16 v[70:73], v[168:171], v[208:211], v[70:73]
	v_mfma_f32_16x16x32_bf16 v[66:69], v[176:179], v[208:211], v[66:69]
	s_setprio 0
	s_barrier
	s_mov_b32 m0, s53
	v_lshl_add_u64 v[148:149], v[148:149], 0, s[70:71]
	ds_read_b128 v[180:183], v139 offset:49152
	ds_read_b128 v[184:187], v139 offset:50176
	ds_read_b128 v[188:191], v139 offset:51200
	ds_read_b128 v[192:195], v139 offset:52224
	ds_read_b128 v[196:199], v139 offset:53248
	ds_read_b128 v[200:203], v139 offset:54272
	ds_read_b128 v[204:207], v139 offset:55296
	ds_read_b128 v[208:211], v139 offset:56320
	global_load_lds_dwordx4 v[148:149], off
	s_mov_b32 m0, s9
	v_lshl_add_u64 v[148:149], v[150:151], 0, s[70:71]
	global_load_lds_dwordx4 v[148:149], off
	s_mov_b32 m0, s96
	v_lshl_add_u64 v[148:149], s[38:39], 0, v[0:1]
	global_load_lds_dwordx4 v[148:149], off
	s_mov_b32 m0, s92
	v_lshl_add_u64 v[148:149], s[38:39], 0, v[130:131]
	global_load_lds_dwordx4 v[148:149], off
	s_mov_b32 m0, s46
	v_lshl_add_u64 v[148:149], v[212:213], 0, s[70:71]
	global_load_lds_dwordx4 v[148:149], off
	s_mov_b32 m0, s47
	v_lshl_add_u64 v[148:149], v[214:215], 0, s[70:71]
	global_load_lds_dwordx4 v[148:149], off
	s_waitcnt vmcnt(8)
	s_waitcnt lgkmcnt(0)
	s_setprio 1
	s_barrier
	v_mfma_f32_16x16x32_bf16 v[62:65], v[140:143], v[180:183], v[62:65]
	v_mfma_f32_16x16x32_bf16 v[58:61], v[156:159], v[180:183], v[58:61]
	v_mfma_f32_16x16x32_bf16 v[54:57], v[140:143], v[188:191], v[54:57]
	v_mfma_f32_16x16x32_bf16 v[50:53], v[156:159], v[188:191], v[50:53]
	v_mfma_f32_16x16x32_bf16 v[38:41], v[140:143], v[196:199], v[38:41]
	v_mfma_f32_16x16x32_bf16 v[34:37], v[156:159], v[196:199], v[34:37]
	v_mfma_f32_16x16x32_bf16 v[22:25], v[140:143], v[204:207], v[22:25]
	v_mfma_f32_16x16x32_bf16 v[18:21], v[156:159], v[204:207], v[18:21]
	v_mfma_f32_16x16x32_bf16 v[62:65], v[144:147], v[184:187], v[62:65]
	v_mfma_f32_16x16x32_bf16 v[58:61], v[160:163], v[184:187], v[58:61]
	v_mfma_f32_16x16x32_bf16 v[54:57], v[144:147], v[192:195], v[54:57]
	v_mfma_f32_16x16x32_bf16 v[50:53], v[160:163], v[192:195], v[50:53]
	v_mfma_f32_16x16x32_bf16 v[38:41], v[144:147], v[200:203], v[38:41]
	v_mfma_f32_16x16x32_bf16 v[34:37], v[160:163], v[200:203], v[34:37]
	v_mfma_f32_16x16x32_bf16 v[22:25], v[144:147], v[208:211], v[22:25]
	v_mfma_f32_16x16x32_bf16 v[18:21], v[160:163], v[208:211], v[18:21]
	v_mfma_f32_16x16x32_bf16 v[46:49], v[164:167], v[180:183], v[46:49]
	v_mfma_f32_16x16x32_bf16 v[42:45], v[172:175], v[180:183], v[42:45]
	v_mfma_f32_16x16x32_bf16 v[30:33], v[164:167], v[188:191], v[30:33]
	v_mfma_f32_16x16x32_bf16 v[26:29], v[172:175], v[188:191], v[26:29]
	v_mfma_f32_16x16x32_bf16 v[14:17], v[164:167], v[196:199], v[14:17]
	v_mfma_f32_16x16x32_bf16 v[10:13], v[172:175], v[196:199], v[10:13]
	v_mfma_f32_16x16x32_bf16 v[6:9], v[164:167], v[204:207], v[6:9]
	v_mfma_f32_16x16x32_bf16 v[2:5], v[172:175], v[204:207], v[2:5]
	v_mfma_f32_16x16x32_bf16 v[46:49], v[168:171], v[184:187], v[46:49]
	v_mfma_f32_16x16x32_bf16 v[42:45], v[176:179], v[184:187], v[42:45]
	v_mfma_f32_16x16x32_bf16 v[30:33], v[168:171], v[192:195], v[30:33]
	v_mfma_f32_16x16x32_bf16 v[26:29], v[176:179], v[192:195], v[26:29]
	v_mfma_f32_16x16x32_bf16 v[14:17], v[168:171], v[200:203], v[14:17]
	v_mfma_f32_16x16x32_bf16 v[10:13], v[176:179], v[200:203], v[10:13]
	v_mfma_f32_16x16x32_bf16 v[6:9], v[168:171], v[208:211], v[6:9]
	v_mfma_f32_16x16x32_bf16 v[2:5], v[176:179], v[208:211], v[2:5]
	s_setprio 0
	s_barrier
	s_movk_i32 s9, 0x100
	s_andn2_b64 vcc, exec, s[4:5]
	s_mov_b64 s[38:39], -1
	s_mov_b64 s[4:5], 0
	s_cbranch_vccz .LBB0_376
	s_and_b64 vcc, exec, s[14:15]
	s_cbranch_vccz .LBB0_379
	s_barrier

.LBB0_393:
	s_ashr_i32 s19, s18, 31
	s_lshl_b64 s[24:25], s[18:19], 16
	s_add_u32 s24, s29, s24
	s_addc_u32 s25, s38, s25
	s_and_b64 s[4:5], s[4:5], exec
	s_cselect_b32 s5, s25, s27
	s_cselect_b32 s4, s24, s26
	s_add_i32 s19, 0, 0x10000
	s_add_i32 s48, 0, 0x14000
	v_add_u32_e32 v14, s19, v137
	v_add_u32_e32 v30, s48, v137
	.p2align 6
	ds_read_b128 v[2:5], v14
	ds_read_b128 v[6:9], v14 offset:1024
	ds_read_b128 v[10:13], v14 offset:2048
	ds_read_b128 v[14:17], v14 offset:3072
	ds_read_b128 v[18:21], v30
	ds_read_b128 v[22:25], v30 offset:1024
	ds_read_b128 v[26:29], v30 offset:2048
	ds_read_b128 v[30:33], v30 offset:3072
	s_add_u32 s26, s36, 0x58080
	s_addc_u32 s27, s37, 0
	v_lshl_add_u64 v[66:67], s[26:27], 0, v[134:135]
	s_add_i32 m0, s40, 0xc000
	ds_read_b128 v[34:37], v139
	ds_read_b128 v[38:41], v139 offset:1024
	ds_read_b128 v[42:45], v139 offset:2048
	ds_read_b128 v[46:49], v139 offset:3072
	ds_read_b128 v[50:53], v139 offset:4096
	ds_read_b128 v[54:57], v139 offset:5120
	ds_read_b128 v[58:61], v139 offset:6144
	ds_read_b128 v[62:65], v139 offset:7168
	global_load_lds_dwordx4 v[66:67], off
	s_add_i32 m0, s40, 0xe000
	v_lshl_add_u64 v[66:67], s[26:27], 0, v[132:133]
	global_load_lds_dwordx4 v[66:67], off
	s_waitcnt vmcnt(8)
	s_waitcnt lgkmcnt(0)
	s_setprio 1
	s_barrier
	v_mfma_f32_16x16x32_bf16 v[66:69], v[2:5], v[34:37], 0
	v_mfma_f32_16x16x32_bf16 v[70:73], v[10:13], v[34:37], 0
	v_mfma_f32_16x16x32_bf16 v[74:77], v[2:5], v[42:45], 0
	v_mfma_f32_16x16x32_bf16 v[78:81], v[10:13], v[42:45], 0
	v_mfma_f32_16x16x32_bf16 v[82:85], v[2:5], v[50:53], 0
	v_mfma_f32_16x16x32_bf16 v[86:89], v[10:13], v[50:53], 0
	v_mfma_f32_16x16x32_bf16 v[90:93], v[2:5], v[58:61], 0
	v_mfma_f32_16x16x32_bf16 v[94:97], v[10:13], v[58:61], 0
	v_mfma_f32_16x16x32_bf16 v[66:69], v[6:9], v[38:41], v[66:69]
	v_mfma_f32_16x16x32_bf16 v[70:73], v[14:17], v[38:41], v[70:73]
	v_mfma_f32_16x16x32_bf16 v[74:77], v[6:9], v[46:49], v[74:77]
	v_mfma_f32_16x16x32_bf16 v[78:81], v[14:17], v[46:49], v[78:81]
	v_mfma_f32_16x16x32_bf16 v[82:85], v[6:9], v[54:57], v[82:85]
	v_mfma_f32_16x16x32_bf16 v[86:89], v[14:17], v[54:57], v[86:89]
	v_mfma_f32_16x16x32_bf16 v[90:93], v[6:9], v[62:65], v[90:93]
	v_mfma_f32_16x16x32_bf16 v[94:97], v[14:17], v[62:65], v[94:97]
	v_mfma_f32_16x16x32_bf16 v[98:101], v[18:21], v[34:37], 0
	v_mfma_f32_16x16x32_bf16 v[34:37], v[26:29], v[34:37], 0
	v_mfma_f32_16x16x32_bf16 v[98:101], v[22:25], v[38:41], v[98:101]
	v_mfma_f32_16x16x32_bf16 v[34:37], v[30:33], v[38:41], v[34:37]
	v_mfma_f32_16x16x32_bf16 v[38:41], v[18:21], v[42:45], 0
	v_mfma_f32_16x16x32_bf16 v[42:45], v[26:29], v[42:45], 0
	v_mfma_f32_16x16x32_bf16 v[102:105], v[30:33], v[46:49], v[42:45]
	v_mfma_f32_16x16x32_bf16 v[42:45], v[18:21], v[50:53], 0
	v_mfma_f32_16x16x32_bf16 v[114:117], v[22:25], v[54:57], v[42:45]
	v_mfma_f32_16x16x32_bf16 v[42:45], v[26:29], v[50:53], 0
	v_mfma_f32_16x16x32_bf16 v[50:53], v[30:33], v[54:57], v[42:45]
	v_mfma_f32_16x16x32_bf16 v[42:45], v[18:21], v[58:61], 0
	v_mfma_f32_16x16x32_bf16 v[54:57], v[22:25], v[62:65], v[42:45]
	v_mfma_f32_16x16x32_bf16 v[42:45], v[26:29], v[58:61], 0
	v_mfma_f32_16x16x32_bf16 v[38:41], v[22:25], v[46:49], v[38:41]
	v_mfma_f32_16x16x32_bf16 v[58:61], v[30:33], v[62:65], v[42:45]
	s_setprio 0
	s_barrier
	s_add_i32 s19, s19, s39
	v_lshl_add_u64 v[148:149], s[4:5], 0, v[0:1]
	s_mov_b32 m0, s19
	s_nop 0
	ds_read_b128 v[42:45], v139 offset:16384
	ds_read_b128 v[46:49], v139 offset:17408
	ds_read_b128 v[62:65], v139 offset:18432
	ds_read_b128 v[106:109], v139 offset:19456
	ds_read_b128 v[110:113], v139 offset:20480
	ds_read_b128 v[118:121], v139 offset:21504
	ds_read_b128 v[122:125], v139 offset:22528
	ds_read_b128 v[126:129], v139 offset:23552
	global_load_lds_dwordx4 v[148:149], off
	s_add_i32 m0, s19, 0x2000
	s_add_u32 s26, s4, 0x8000
	v_lshl_add_u64 v[150:151], s[4:5], 0, v[130:131]
	s_addc_u32 s27, s5, 0
	s_add_i32 s19, s48, s39
	global_load_lds_dwordx4 v[150:151], off
	v_lshl_add_u64 v[140:141], s[26:27], 0, v[0:1]
	s_mov_b32 m0, s19
	v_lshl_add_u64 v[252:253], s[22:23], 0, v[134:135]
	global_load_lds_dwordx4 v[140:141], off
	v_lshl_add_u64 v[140:141], s[26:27], 0, v[130:131]
	s_add_i32 m0, s19, 0x2000
	v_lshl_add_u64 v[242:243], s[22:23], 0, v[132:133]
	global_load_lds_dwordx4 v[140:141], off
	s_mov_b32 m0, s40
	s_nop 0
	global_load_lds_dwordx4 v[252:253], off
	s_mov_b32 m0, s41
	s_nop 0
	global_load_lds_dwordx4 v[242:243], off
	s_waitcnt vmcnt(8)
	s_waitcnt lgkmcnt(0)
	s_setprio 1
	s_barrier
	v_mfma_f32_16x16x32_bf16 v[140:143], v[2:5], v[42:45], 0
	v_mfma_f32_16x16x32_bf16 v[156:159], v[2:5], v[62:65], 0
	v_mfma_f32_16x16x32_bf16 v[164:167], v[2:5], v[110:113], 0
	v_mfma_f32_16x16x32_bf16 v[2:5], v[2:5], v[122:125], 0
	v_mfma_f32_16x16x32_bf16 v[140:143], v[6:9], v[46:49], v[140:143]
	v_mfma_f32_16x16x32_bf16 v[156:159], v[6:9], v[106:109], v[156:159]
	v_mfma_f32_16x16x32_bf16 v[164:167], v[6:9], v[118:121], v[164:167]
	v_mfma_f32_16x16x32_bf16 v[2:5], v[6:9], v[126:129], v[2:5]
	v_mfma_f32_16x16x32_bf16 v[6:9], v[10:13], v[122:125], 0
	v_mfma_f32_16x16x32_bf16 v[144:147], v[10:13], v[42:45], 0
	v_mfma_f32_16x16x32_bf16 v[160:163], v[10:13], v[62:65], 0
	v_mfma_f32_16x16x32_bf16 v[168:171], v[10:13], v[110:113], 0
	v_mfma_f32_16x16x32_bf16 v[6:9], v[14:17], v[126:129], v[6:9]
	v_mfma_f32_16x16x32_bf16 v[144:147], v[14:17], v[46:49], v[144:147]
	v_mfma_f32_16x16x32_bf16 v[160:163], v[14:17], v[106:109], v[160:163]
	v_mfma_f32_16x16x32_bf16 v[168:171], v[14:17], v[118:121], v[168:171]
	v_mfma_f32_16x16x32_bf16 v[10:13], v[18:21], v[42:45], 0
	v_mfma_f32_16x16x32_bf16 v[172:175], v[22:25], v[46:49], v[10:13]
	v_mfma_f32_16x16x32_bf16 v[10:13], v[26:29], v[42:45], 0
	v_mfma_f32_16x16x32_bf16 v[176:179], v[30:33], v[46:49], v[10:13]
	v_mfma_f32_16x16x32_bf16 v[10:13], v[18:21], v[62:65], 0
	v_mfma_f32_16x16x32_bf16 v[180:183], v[22:25], v[106:109], v[10:13]
	v_mfma_f32_16x16x32_bf16 v[10:13], v[26:29], v[62:65], 0
	v_mfma_f32_16x16x32_bf16 v[184:187], v[30:33], v[106:109], v[10:13]
	v_mfma_f32_16x16x32_bf16 v[10:13], v[18:21], v[110:113], 0
	v_mfma_f32_16x16x32_bf16 v[188:191], v[22:25], v[118:121], v[10:13]
	v_mfma_f32_16x16x32_bf16 v[10:13], v[26:29], v[110:113], 0
	v_mfma_f32_16x16x32_bf16 v[192:195], v[30:33], v[118:121], v[10:13]
	v_mfma_f32_16x16x32_bf16 v[10:13], v[18:21], v[122:125], 0
	v_mfma_f32_16x16x32_bf16 v[18:21], v[22:25], v[126:129], v[10:13]
	v_mfma_f32_16x16x32_bf16 v[10:13], v[26:29], v[122:125], 0
	v_mfma_f32_16x16x32_bf16 v[22:25], v[30:33], v[126:129], v[10:13]
	s_setprio 0
	s_barrier
	s_add_i32 s19, 0, 0x18000
	s_nop 3
	v_add_u32_e32 v10, s19, v137
	s_add_i32 s36, 0, 0x1c000
	ds_read_b128 v[118:121], v10
	ds_read_b128 v[196:199], v10 offset:1024
	ds_read_b128 v[200:203], v10 offset:2048
	ds_read_b128 v[204:207], v10 offset:3072
	v_add_u32_e32 v10, s36, v137
	ds_read_b128 v[208:211], v10
	ds_read_b128 v[212:215], v10 offset:1024
	ds_read_b128 v[216:219], v10 offset:2048
	ds_read_b128 v[220:223], v10 offset:3072
	s_add_u32 s26, s22, 0x58000
	s_addc_u32 s27, s23, 0
	s_mov_b32 m0, s42
	v_lshl_add_u64 v[10:11], s[26:27], 0, v[134:135]
	ds_read_b128 v[26:29], v139 offset:32768
	ds_read_b128 v[30:33], v139 offset:33792
	ds_read_b128 v[62:65], v139 offset:34816
	ds_read_b128 v[224:227], v139 offset:35840
	ds_read_b128 v[228:231], v139 offset:36864
	ds_read_b128 v[232:235], v139 offset:37888
	ds_read_b128 v[236:239], v139 offset:38912
	ds_read_b128 v[248:251], v139 offset:39936
	global_load_lds_dwordx4 v[10:11], off
	s_mov_b32 m0, s43
	v_lshl_add_u64 v[10:11], s[26:27], 0, v[132:133]
	global_load_lds_dwordx4 v[10:11], off
	s_waitcnt vmcnt(8)
	s_waitcnt lgkmcnt(0)
	s_setprio 1
	s_barrier
	v_mfma_f32_16x16x32_bf16 v[10:13], v[118:121], v[26:29], v[66:69]
	v_mfma_f32_16x16x32_bf16 v[106:109], v[196:199], v[30:33], v[10:13]
	v_mfma_f32_16x16x32_bf16 v[10:13], v[200:203], v[26:29], v[70:73]
	v_mfma_f32_16x16x32_bf16 v[110:113], v[204:207], v[30:33], v[10:13]
	v_mfma_f32_16x16x32_bf16 v[10:13], v[118:121], v[62:65], v[74:77]
	v_mfma_f32_16x16x32_bf16 v[74:77], v[196:199], v[224:227], v[10:13]
	v_mfma_f32_16x16x32_bf16 v[10:13], v[200:203], v[62:65], v[78:81]
	v_mfma_f32_16x16x32_bf16 v[78:81], v[204:207], v[224:227], v[10:13]
	v_mfma_f32_16x16x32_bf16 v[10:13], v[118:121], v[228:231], v[82:85]
	v_mfma_f32_16x16x32_bf16 v[42:45], v[196:199], v[232:235], v[10:13]
	v_mfma_f32_16x16x32_bf16 v[10:13], v[200:203], v[228:231], v[86:89]
	v_mfma_f32_16x16x32_bf16 v[46:49], v[204:207], v[232:235], v[10:13]
	v_mfma_f32_16x16x32_bf16 v[10:13], v[118:121], v[236:239], v[90:93]
	v_mfma_f32_16x16x32_bf16 v[14:17], v[200:203], v[236:239], v[94:97]
	v_mfma_f32_16x16x32_bf16 v[10:13], v[196:199], v[248:251], v[10:13]
	v_mfma_f32_16x16x32_bf16 v[14:17], v[204:207], v[248:251], v[14:17]
	v_mfma_f32_16x16x32_bf16 v[66:69], v[208:211], v[26:29], v[98:101]
	v_mfma_f32_16x16x32_bf16 v[26:29], v[216:219], v[26:29], v[34:37]
	v_mfma_f32_16x16x32_bf16 v[126:129], v[220:223], v[30:33], v[26:29]
	v_mfma_f32_16x16x32_bf16 v[26:29], v[208:211], v[62:65], v[38:41]
	v_mfma_f32_16x16x32_bf16 v[98:101], v[212:215], v[224:227], v[26:29]
	v_mfma_f32_16x16x32_bf16 v[26:29], v[216:219], v[62:65], v[102:105]
	v_mfma_f32_16x16x32_bf16 v[102:105], v[220:223], v[224:227], v[26:29]
	v_mfma_f32_16x16x32_bf16 v[26:29], v[208:211], v[228:231], v[114:117]
	v_mfma_f32_16x16x32_bf16 v[122:125], v[212:215], v[30:33], v[66:69]
	v_mfma_f32_16x16x32_bf16 v[66:69], v[212:215], v[232:235], v[26:29]
	v_mfma_f32_16x16x32_bf16 v[26:29], v[216:219], v[228:231], v[50:53]
	v_mfma_f32_16x16x32_bf16 v[70:73], v[220:223], v[232:235], v[26:29]
	v_mfma_f32_16x16x32_bf16 v[26:29], v[208:211], v[236:239], v[54:57]
	v_mfma_f32_16x16x32_bf16 v[34:37], v[212:215], v[248:251], v[26:29]
	v_mfma_f32_16x16x32_bf16 v[26:29], v[216:219], v[236:239], v[58:61]
	v_mfma_f32_16x16x32_bf16 v[38:41], v[220:223], v[248:251], v[26:29]
	s_setprio 0
	s_barrier
	s_add_i32 s19, s19, s39
	s_nop 3
	v_lshl_add_u64 v[26:27], v[148:149], 0, s[70:71]
	s_mov_b32 m0, s19
	ds_read_b128 v[50:53], v139 offset:49152
	ds_read_b128 v[54:57], v139 offset:50176
	ds_read_b128 v[86:89], v139 offset:51200
	ds_read_b128 v[224:227], v139 offset:52224
	ds_read_b128 v[228:231], v139 offset:53248
	ds_read_b128 v[232:235], v139 offset:54272
	ds_read_b128 v[236:239], v139 offset:55296
	ds_read_b128 v[248:251], v139 offset:56320
	global_load_lds_dwordx4 v[26:27], off
	s_add_i32 m0, s19, 0x2000
	s_add_u32 s4, s4, 0x8080
	v_lshl_add_u64 v[26:27], v[150:151], 0, s[70:71]
	s_addc_u32 s5, s5, 0
	s_add_i32 s19, s36, s39
	global_load_lds_dwordx4 v[26:27], off
	s_mov_b32 m0, s19
	v_lshl_add_u64 v[26:27], s[4:5], 0, v[0:1]
	global_load_lds_dwordx4 v[26:27], off
	s_add_i32 m0, s19, 0x2000
	v_lshl_add_u64 v[26:27], s[4:5], 0, v[130:131]
	global_load_lds_dwordx4 v[26:27], off
	s_mov_b32 m0, s44
	v_lshl_add_u64 v[26:27], v[252:253], 0, s[70:71]
	global_load_lds_dwordx4 v[26:27], off
	s_mov_b32 m0, s45
	v_lshl_add_u64 v[26:27], v[242:243], 0, s[70:71]
	global_load_lds_dwordx4 v[26:27], off
	s_waitcnt vmcnt(8)
	s_waitcnt lgkmcnt(0)
	s_setprio 1
	s_barrier
	v_mfma_f32_16x16x32_bf16 v[26:29], v[118:121], v[50:53], v[140:143]
	v_mfma_f32_16x16x32_bf16 v[90:93], v[196:199], v[54:57], v[26:29]
	v_mfma_f32_16x16x32_bf16 v[26:29], v[200:203], v[50:53], v[144:147]
	v_mfma_f32_16x16x32_bf16 v[94:97], v[204:207], v[54:57], v[26:29]
	v_mfma_f32_16x16x32_bf16 v[26:29], v[118:121], v[86:89], v[156:159]
	v_mfma_f32_16x16x32_bf16 v[58:61], v[196:199], v[224:227], v[26:29]
	v_mfma_f32_16x16x32_bf16 v[26:29], v[200:203], v[86:89], v[160:163]
	v_mfma_f32_16x16x32_bf16 v[62:65], v[204:207], v[224:227], v[26:29]
	v_mfma_f32_16x16x32_bf16 v[26:29], v[118:121], v[228:231], v[164:167]
	v_mfma_f32_16x16x32_bf16 v[30:33], v[200:203], v[228:231], v[168:171]
	v_mfma_f32_16x16x32_bf16 v[2:5], v[118:121], v[236:239], v[2:5]
	v_mfma_f32_16x16x32_bf16 v[6:9], v[200:203], v[236:239], v[6:9]
	v_mfma_f32_16x16x32_bf16 v[26:29], v[196:199], v[232:235], v[26:29]
	v_mfma_f32_16x16x32_bf16 v[30:33], v[204:207], v[232:235], v[30:33]
	v_mfma_f32_16x16x32_bf16 v[2:5], v[196:199], v[248:251], v[2:5]
	v_mfma_f32_16x16x32_bf16 v[6:9], v[204:207], v[248:251], v[6:9]
	v_mfma_f32_16x16x32_bf16 v[82:85], v[208:211], v[50:53], v[172:175]
	v_mfma_f32_16x16x32_bf16 v[50:53], v[216:219], v[50:53], v[176:179]
	v_mfma_f32_16x16x32_bf16 v[118:121], v[220:223], v[54:57], v[50:53]
	v_mfma_f32_16x16x32_bf16 v[50:53], v[208:211], v[86:89], v[180:183]
	v_mfma_f32_16x16x32_bf16 v[114:117], v[212:215], v[54:57], v[82:85]
	v_mfma_f32_16x16x32_bf16 v[82:85], v[212:215], v[224:227], v[50:53]
	v_mfma_f32_16x16x32_bf16 v[50:53], v[216:219], v[86:89], v[184:187]
	v_mfma_f32_16x16x32_bf16 v[86:89], v[220:223], v[224:227], v[50:53]
	v_mfma_f32_16x16x32_bf16 v[50:53], v[208:211], v[228:231], v[188:191]
	v_mfma_f32_16x16x32_bf16 v[54:57], v[216:219], v[228:231], v[192:195]
	v_mfma_f32_16x16x32_bf16 v[18:21], v[208:211], v[236:239], v[18:21]
	v_mfma_f32_16x16x32_bf16 v[22:25], v[216:219], v[236:239], v[22:25]
	v_mfma_f32_16x16x32_bf16 v[50:53], v[212:215], v[232:235], v[50:53]
	v_mfma_f32_16x16x32_bf16 v[54:57], v[220:223], v[232:235], v[54:57]
	v_mfma_f32_16x16x32_bf16 v[18:21], v[212:215], v[248:251], v[18:21]
	v_mfma_f32_16x16x32_bf16 v[22:25], v[220:223], v[248:251], v[22:25]
	s_setprio 0
	s_barrier
	s_andn2_b64 vcc, exec, s[14:15]
	s_cbranch_vccnz .LBB0_395
	s_barrier

.LBB0_701:
	s_add_i32 s75, s26, 2
	s_add_u32 s9, s60, 0xfffc0080
	s_addc_u32 s27, s61, -1
	s_add_i32 s78, 0, 0x10000
	s_cmp_eq_u32 s19, s26
	s_cselect_b32 s73, s23, s27
	s_cselect_b32 s72, s22, s9
	s_cselect_b32 s27, s25, s29
	s_cselect_b32 s26, s24, s28
	s_add_i32 s9, 0, 0x14000
	s_waitcnt vmcnt(0)
	v_add_u32_e32 v142, s78, v177
	v_add_u32_e32 v148, s9, v177
	ds_read_b128 v[130:133], v142
	ds_read_b128 v[134:137], v142 offset:1024
	ds_read_b128 v[138:141], v142 offset:2048
	ds_read_b128 v[142:145], v142 offset:3072
	ds_read_b128 v[164:167], v148
	ds_read_b128 v[168:171], v148 offset:1024
	ds_read_b128 v[172:175], v148 offset:2048
	ds_read_b128 v[180:183], v148 offset:3072
	v_lshl_add_u64 v[148:149], s[60:61], 0, v[160:161]
	s_add_i32 m0, s37, 0xc000
	ds_read_b128 v[184:187], v179
	ds_read_b128 v[188:191], v179 offset:1024
	ds_read_b128 v[192:195], v179 offset:2048
	ds_read_b128 v[196:199], v179 offset:3072
	ds_read_b128 v[200:203], v179 offset:4096
	ds_read_b128 v[204:207], v179 offset:5120
	ds_read_b128 v[208:211], v179 offset:6144
	ds_read_b128 v[212:215], v179 offset:7168
	global_load_lds_dwordx4 v[148:149], off
	s_add_i32 m0, s37, 0xe000
	v_lshl_add_u64 v[148:149], s[60:61], 0, v[162:163]
	global_load_lds_dwordx4 v[148:149], off
	s_waitcnt vmcnt(8)
	s_waitcnt lgkmcnt(0)
	s_setprio 1
	s_barrier
	v_mfma_f32_16x16x32_bf16 v[126:129], v[130:133], v[184:187], v[126:129]
	v_mfma_f32_16x16x32_bf16 v[122:125], v[138:141], v[184:187], v[122:125]
	v_mfma_f32_16x16x32_bf16 v[110:113], v[130:133], v[192:195], v[110:113]
	v_mfma_f32_16x16x32_bf16 v[106:109], v[138:141], v[192:195], v[106:109]
	v_mfma_f32_16x16x32_bf16 v[94:97], v[130:133], v[200:203], v[94:97]
	v_mfma_f32_16x16x32_bf16 v[90:93], v[138:141], v[200:203], v[90:93]
	v_mfma_f32_16x16x32_bf16 v[78:81], v[130:133], v[208:211], v[78:81]
	v_mfma_f32_16x16x32_bf16 v[74:77], v[138:141], v[208:211], v[74:77]
	v_mfma_f32_16x16x32_bf16 v[126:129], v[134:137], v[188:191], v[126:129]
	v_mfma_f32_16x16x32_bf16 v[122:125], v[142:145], v[188:191], v[122:125]
	v_mfma_f32_16x16x32_bf16 v[110:113], v[134:137], v[196:199], v[110:113]
	v_mfma_f32_16x16x32_bf16 v[106:109], v[142:145], v[196:199], v[106:109]
	v_mfma_f32_16x16x32_bf16 v[94:97], v[134:137], v[204:207], v[94:97]
	v_mfma_f32_16x16x32_bf16 v[90:93], v[142:145], v[204:207], v[90:93]
	v_mfma_f32_16x16x32_bf16 v[78:81], v[134:137], v[212:215], v[78:81]
	v_mfma_f32_16x16x32_bf16 v[74:77], v[142:145], v[212:215], v[74:77]
	v_mfma_f32_16x16x32_bf16 v[118:121], v[164:167], v[184:187], v[118:121]
	v_mfma_f32_16x16x32_bf16 v[114:117], v[172:175], v[184:187], v[114:117]
	v_mfma_f32_16x16x32_bf16 v[102:105], v[164:167], v[192:195], v[102:105]
	v_mfma_f32_16x16x32_bf16 v[98:101], v[172:175], v[192:195], v[98:101]
	v_mfma_f32_16x16x32_bf16 v[86:89], v[164:167], v[200:203], v[86:89]
	v_mfma_f32_16x16x32_bf16 v[82:85], v[172:175], v[200:203], v[82:85]
	v_mfma_f32_16x16x32_bf16 v[70:73], v[164:167], v[208:211], v[70:73]
	v_mfma_f32_16x16x32_bf16 v[66:69], v[172:175], v[208:211], v[66:69]
	v_mfma_f32_16x16x32_bf16 v[118:121], v[168:171], v[188:191], v[118:121]
	v_mfma_f32_16x16x32_bf16 v[114:117], v[180:183], v[188:191], v[114:117]
	v_mfma_f32_16x16x32_bf16 v[102:105], v[168:171], v[196:199], v[102:105]
	v_mfma_f32_16x16x32_bf16 v[98:101], v[180:183], v[196:199], v[98:101]
	v_mfma_f32_16x16x32_bf16 v[86:89], v[168:171], v[204:207], v[86:89]
	v_mfma_f32_16x16x32_bf16 v[82:85], v[180:183], v[204:207], v[82:85]
	v_mfma_f32_16x16x32_bf16 v[70:73], v[168:171], v[212:215], v[70:73]
	v_mfma_f32_16x16x32_bf16 v[66:69], v[180:183], v[212:215], v[66:69]
	s_setprio 0
	s_barrier
	s_add_i32 s78, s78, s41
	v_lshl_add_u64 v[148:149], s[26:27], 0, v[0:1]
	s_mov_b32 m0, s78
	ds_read_b128 v[184:187], v179 offset:16384
	ds_read_b128 v[188:191], v179 offset:17408
	ds_read_b128 v[192:195], v179 offset:18432
	ds_read_b128 v[196:199], v179 offset:19456
	ds_read_b128 v[200:203], v179 offset:20480
	ds_read_b128 v[204:207], v179 offset:21504
	ds_read_b128 v[208:211], v179 offset:22528
	ds_read_b128 v[212:215], v179 offset:23552
	global_load_lds_dwordx4 v[148:149], off
	s_add_i32 m0, s78, 0x2000
	s_add_u32 s78, s26, 0x40000
	v_lshl_add_u64 v[150:151], s[26:27], 0, v[158:159]
	s_addc_u32 s79, s27, 0
	s_add_i32 s9, s9, s41
	global_load_lds_dwordx4 v[150:151], off
	v_lshl_add_u64 v[216:217], s[78:79], 0, v[0:1]
	s_mov_b32 m0, s9
	v_lshl_add_u64 v[218:219], s[72:73], 0, v[156:157]
	global_load_lds_dwordx4 v[216:217], off
	s_add_i32 m0, s9, 0x2000
	v_lshl_add_u64 v[216:217], s[78:79], 0, v[158:159]
	global_load_lds_dwordx4 v[216:217], off
	s_mov_b32 m0, s37
	v_lshl_add_u64 v[216:217], s[72:73], 0, v[146:147]
	global_load_lds_dwordx4 v[216:217], off
	s_mov_b32 m0, s39
	s_nop 0
	global_load_lds_dwordx4 v[218:219], off
	s_waitcnt vmcnt(8)
	s_waitcnt lgkmcnt(0)
	s_setprio 1
	s_barrier
	v_mfma_f32_16x16x32_bf16 v[62:65], v[130:133], v[184:187], v[62:65]
	v_mfma_f32_16x16x32_bf16 v[58:61], v[138:141], v[184:187], v[58:61]
	v_mfma_f32_16x16x32_bf16 v[46:49], v[130:133], v[192:195], v[46:49]
	v_mfma_f32_16x16x32_bf16 v[42:45], v[138:141], v[192:195], v[42:45]
	v_mfma_f32_16x16x32_bf16 v[30:33], v[130:133], v[200:203], v[30:33]
	v_mfma_f32_16x16x32_bf16 v[26:29], v[138:141], v[200:203], v[26:29]
	v_mfma_f32_16x16x32_bf16 v[14:17], v[130:133], v[208:211], v[14:17]
	v_mfma_f32_16x16x32_bf16 v[10:13], v[138:141], v[208:211], v[10:13]
	v_mfma_f32_16x16x32_bf16 v[62:65], v[134:137], v[188:191], v[62:65]
	v_mfma_f32_16x16x32_bf16 v[58:61], v[142:145], v[188:191], v[58:61]
	v_mfma_f32_16x16x32_bf16 v[46:49], v[134:137], v[196:199], v[46:49]
	v_mfma_f32_16x16x32_bf16 v[42:45], v[142:145], v[196:199], v[42:45]
	v_mfma_f32_16x16x32_bf16 v[30:33], v[134:137], v[204:207], v[30:33]
	v_mfma_f32_16x16x32_bf16 v[26:29], v[142:145], v[204:207], v[26:29]
	v_mfma_f32_16x16x32_bf16 v[14:17], v[134:137], v[212:215], v[14:17]
	v_mfma_f32_16x16x32_bf16 v[10:13], v[142:145], v[212:215], v[10:13]
	v_mfma_f32_16x16x32_bf16 v[54:57], v[164:167], v[184:187], v[54:57]
	v_mfma_f32_16x16x32_bf16 v[50:53], v[172:175], v[184:187], v[50:53]
	v_mfma_f32_16x16x32_bf16 v[38:41], v[164:167], v[192:195], v[38:41]
	v_mfma_f32_16x16x32_bf16 v[34:37], v[172:175], v[192:195], v[34:37]
	v_mfma_f32_16x16x32_bf16 v[22:25], v[164:167], v[200:203], v[22:25]
	v_mfma_f32_16x16x32_bf16 v[18:21], v[172:175], v[200:203], v[18:21]
	v_mfma_f32_16x16x32_bf16 v[6:9], v[164:167], v[208:211], v[6:9]
	v_mfma_f32_16x16x32_bf16 v[2:5], v[172:175], v[208:211], v[2:5]
	v_mfma_f32_16x16x32_bf16 v[54:57], v[168:171], v[188:191], v[54:57]
	v_mfma_f32_16x16x32_bf16 v[50:53], v[180:183], v[188:191], v[50:53]
	v_mfma_f32_16x16x32_bf16 v[38:41], v[168:171], v[196:199], v[38:41]
	v_mfma_f32_16x16x32_bf16 v[34:37], v[180:183], v[196:199], v[34:37]
	v_mfma_f32_16x16x32_bf16 v[22:25], v[168:171], v[204:207], v[22:25]
	v_mfma_f32_16x16x32_bf16 v[18:21], v[180:183], v[204:207], v[18:21]
	v_mfma_f32_16x16x32_bf16 v[6:9], v[168:171], v[212:215], v[6:9]
	v_mfma_f32_16x16x32_bf16 v[2:5], v[180:183], v[212:215], v[2:5]
	s_setprio 0
	s_barrier
	s_add_i32 s9, 0, 0x18000
	s_add_i32 s78, 0, 0x1c000
	v_add_u32_e32 v142, s9, v177
	v_add_u32_e32 v180, s78, v177
	ds_read_b128 v[130:133], v142
	ds_read_b128 v[134:137], v142 offset:1024
	ds_read_b128 v[138:141], v142 offset:2048
	ds_read_b128 v[142:145], v142 offset:3072
	ds_read_b128 v[164:167], v180
	ds_read_b128 v[168:171], v180 offset:1024
	ds_read_b128 v[172:175], v180 offset:2048
	ds_read_b128 v[180:183], v180 offset:3072
	s_add_u32 s72, s72, 0x40000
	s_addc_u32 s73, s73, 0
	s_mov_b32 m0, s44
	v_lshl_add_u64 v[220:221], s[72:73], 0, v[146:147]
	ds_read_b128 v[184:187], v179 offset:32768
	ds_read_b128 v[188:191], v179 offset:33792
	ds_read_b128 v[192:195], v179 offset:34816
	ds_read_b128 v[196:199], v179 offset:35840
	ds_read_b128 v[200:203], v179 offset:36864
	ds_read_b128 v[204:207], v179 offset:37888
	ds_read_b128 v[208:211], v179 offset:38912
	ds_read_b128 v[212:215], v179 offset:39936
	global_load_lds_dwordx4 v[220:221], off
	s_mov_b32 m0, s45
	v_lshl_add_u64 v[220:221], s[72:73], 0, v[156:157]
	global_load_lds_dwordx4 v[220:221], off
	s_waitcnt vmcnt(8)
	s_waitcnt lgkmcnt(0)
	s_setprio 1
	s_barrier
	v_mfma_f32_16x16x32_bf16 v[126:129], v[130:133], v[184:187], v[126:129]
	v_mfma_f32_16x16x32_bf16 v[122:125], v[138:141], v[184:187], v[122:125]
	v_mfma_f32_16x16x32_bf16 v[110:113], v[130:133], v[192:195], v[110:113]
	v_mfma_f32_16x16x32_bf16 v[106:109], v[138:141], v[192:195], v[106:109]
	v_mfma_f32_16x16x32_bf16 v[94:97], v[130:133], v[200:203], v[94:97]
	v_mfma_f32_16x16x32_bf16 v[90:93], v[138:141], v[200:203], v[90:93]
	v_mfma_f32_16x16x32_bf16 v[78:81], v[130:133], v[208:211], v[78:81]
	v_mfma_f32_16x16x32_bf16 v[74:77], v[138:141], v[208:211], v[74:77]
	v_mfma_f32_16x16x32_bf16 v[126:129], v[134:137], v[188:191], v[126:129]
	v_mfma_f32_16x16x32_bf16 v[122:125], v[142:145], v[188:191], v[122:125]
	v_mfma_f32_16x16x32_bf16 v[110:113], v[134:137], v[196:199], v[110:113]
	v_mfma_f32_16x16x32_bf16 v[106:109], v[142:145], v[196:199], v[106:109]
	v_mfma_f32_16x16x32_bf16 v[94:97], v[134:137], v[204:207], v[94:97]
	v_mfma_f32_16x16x32_bf16 v[90:93], v[142:145], v[204:207], v[90:93]
	v_mfma_f32_16x16x32_bf16 v[78:81], v[134:137], v[212:215], v[78:81]
	v_mfma_f32_16x16x32_bf16 v[74:77], v[142:145], v[212:215], v[74:77]
	v_mfma_f32_16x16x32_bf16 v[118:121], v[164:167], v[184:187], v[118:121]
	v_mfma_f32_16x16x32_bf16 v[114:117], v[172:175], v[184:187], v[114:117]
	v_mfma_f32_16x16x32_bf16 v[102:105], v[164:167], v[192:195], v[102:105]
	v_mfma_f32_16x16x32_bf16 v[98:101], v[172:175], v[192:195], v[98:101]
	v_mfma_f32_16x16x32_bf16 v[86:89], v[164:167], v[200:203], v[86:89]
	v_mfma_f32_16x16x32_bf16 v[82:85], v[172:175], v[200:203], v[82:85]
	v_mfma_f32_16x16x32_bf16 v[70:73], v[164:167], v[208:211], v[70:73]
	v_mfma_f32_16x16x32_bf16 v[66:69], v[172:175], v[208:211], v[66:69]
	v_mfma_f32_16x16x32_bf16 v[118:121], v[168:171], v[188:191], v[118:121]
	v_mfma_f32_16x16x32_bf16 v[114:117], v[180:183], v[188:191], v[114:117]
	v_mfma_f32_16x16x32_bf16 v[102:105], v[168:171], v[196:199], v[102:105]
	v_mfma_f32_16x16x32_bf16 v[98:101], v[180:183], v[196:199], v[98:101]
	v_mfma_f32_16x16x32_bf16 v[86:89], v[168:171], v[204:207], v[86:89]
	v_mfma_f32_16x16x32_bf16 v[82:85], v[180:183], v[204:207], v[82:85]
	v_mfma_f32_16x16x32_bf16 v[70:73], v[168:171], v[212:215], v[70:73]
	v_mfma_f32_16x16x32_bf16 v[66:69], v[180:183], v[212:215], v[66:69]
	s_setprio 0
	s_barrier
	s_add_i32 s9, s9, s41
	v_lshl_add_u64 v[148:149], v[148:149], 0, s[70:71]
	s_mov_b32 m0, s9
	ds_read_b128 v[184:187], v179 offset:49152
	ds_read_b128 v[188:191], v179 offset:50176
	ds_read_b128 v[192:195], v179 offset:51200
	ds_read_b128 v[196:199], v179 offset:52224
	ds_read_b128 v[200:203], v179 offset:53248
	ds_read_b128 v[204:207], v179 offset:54272
	ds_read_b128 v[208:211], v179 offset:55296
	ds_read_b128 v[212:215], v179 offset:56320
	global_load_lds_dwordx4 v[148:149], off
	s_add_i32 m0, s9, 0x2000
	s_add_u32 s26, s26, 0x40080
	v_lshl_add_u64 v[148:149], v[150:151], 0, s[70:71]
	s_addc_u32 s27, s27, 0
	s_add_i32 s9, s78, s41
	global_load_lds_dwordx4 v[148:149], off
	s_mov_b32 m0, s9
	v_lshl_add_u64 v[148:149], s[26:27], 0, v[0:1]
	global_load_lds_dwordx4 v[148:149], off
	s_add_i32 m0, s9, 0x2000
	v_lshl_add_u64 v[148:149], s[26:27], 0, v[158:159]
	global_load_lds_dwordx4 v[148:149], off
	s_mov_b32 m0, s50
	v_lshl_add_u64 v[148:149], v[216:217], 0, s[70:71]
	global_load_lds_dwordx4 v[148:149], off
	s_mov_b32 m0, s51
	v_lshl_add_u64 v[148:149], v[218:219], 0, s[70:71]
	global_load_lds_dwordx4 v[148:149], off
	s_waitcnt vmcnt(8)
	s_waitcnt lgkmcnt(0)
	s_setprio 1
	s_barrier
	v_mfma_f32_16x16x32_bf16 v[62:65], v[130:133], v[184:187], v[62:65]
	v_mfma_f32_16x16x32_bf16 v[58:61], v[138:141], v[184:187], v[58:61]
	v_mfma_f32_16x16x32_bf16 v[46:49], v[130:133], v[192:195], v[46:49]
	v_mfma_f32_16x16x32_bf16 v[42:45], v[138:141], v[192:195], v[42:45]
	v_mfma_f32_16x16x32_bf16 v[30:33], v[130:133], v[200:203], v[30:33]
	v_mfma_f32_16x16x32_bf16 v[26:29], v[138:141], v[200:203], v[26:29]
	v_mfma_f32_16x16x32_bf16 v[14:17], v[130:133], v[208:211], v[14:17]
	v_mfma_f32_16x16x32_bf16 v[10:13], v[138:141], v[208:211], v[10:13]
	v_mfma_f32_16x16x32_bf16 v[62:65], v[134:137], v[188:191], v[62:65]
	v_mfma_f32_16x16x32_bf16 v[58:61], v[142:145], v[188:191], v[58:61]
	v_mfma_f32_16x16x32_bf16 v[46:49], v[134:137], v[196:199], v[46:49]
	v_mfma_f32_16x16x32_bf16 v[42:45], v[142:145], v[196:199], v[42:45]
	v_mfma_f32_16x16x32_bf16 v[30:33], v[134:137], v[204:207], v[30:33]
	v_mfma_f32_16x16x32_bf16 v[26:29], v[142:145], v[204:207], v[26:29]
	v_mfma_f32_16x16x32_bf16 v[14:17], v[134:137], v[212:215], v[14:17]
	v_mfma_f32_16x16x32_bf16 v[10:13], v[142:145], v[212:215], v[10:13]
	v_mfma_f32_16x16x32_bf16 v[54:57], v[164:167], v[184:187], v[54:57]
	v_mfma_f32_16x16x32_bf16 v[50:53], v[172:175], v[184:187], v[50:53]
	v_mfma_f32_16x16x32_bf16 v[38:41], v[164:167], v[192:195], v[38:41]
	v_mfma_f32_16x16x32_bf16 v[34:37], v[172:175], v[192:195], v[34:37]
	v_mfma_f32_16x16x32_bf16 v[22:25], v[164:167], v[200:203], v[22:25]
	v_mfma_f32_16x16x32_bf16 v[18:21], v[172:175], v[200:203], v[18:21]
	v_mfma_f32_16x16x32_bf16 v[6:9], v[164:167], v[208:211], v[6:9]
	v_mfma_f32_16x16x32_bf16 v[2:5], v[172:175], v[208:211], v[2:5]
	v_mfma_f32_16x16x32_bf16 v[54:57], v[168:171], v[188:191], v[54:57]
	v_mfma_f32_16x16x32_bf16 v[50:53], v[180:183], v[188:191], v[50:53]
	v_mfma_f32_16x16x32_bf16 v[38:41], v[168:171], v[196:199], v[38:41]
	v_mfma_f32_16x16x32_bf16 v[34:37], v[180:183], v[196:199], v[34:37]
	v_mfma_f32_16x16x32_bf16 v[22:25], v[168:171], v[204:207], v[22:25]
	v_mfma_f32_16x16x32_bf16 v[18:21], v[180:183], v[204:207], v[18:21]
	v_mfma_f32_16x16x32_bf16 v[6:9], v[168:171], v[212:215], v[6:9]
	v_mfma_f32_16x16x32_bf16 v[2:5], v[180:183], v[212:215], v[2:5]
	s_setprio 0
	s_barrier
	s_add_u32 s60, s60, 0x100
	s_addc_u32 s61, s61, 0
	s_add_u32 s28, s28, 0x100
	s_addc_u32 s29, s29, 0
	s_cmp_ge_u32 s75, s17
	s_mov_b32 s26, s75
	s_cbranch_scc0 .LBB0_701
	s_and_b64 vcc, exec, s[14:15]
	s_cbranch_vccz .LBB0_704

.LBB0_846:
	s_add_u32 s9, s96, 0xfffc0080
	s_addc_u32 s38, s97, -1
	s_add_i32 s78, 0, 0x10000
	s_cmp_eq_u32 s75, 12
	s_cselect_b32 vcc_hi, s25, s38
	s_cselect_b32 vcc_lo, s28, s9
	v_add_u32_e32 v148, s78, v145
	s_cselect_b32 s39, s23, s61
	s_cselect_b32 s38, s29, s53
	s_add_i32 s9, 0, 0x14000
	ds_read_b128 v[140:143], v148
	ds_read_b128 v[156:159], v148 offset:1024
	ds_read_b128 v[160:163], v148 offset:2048
	ds_read_b128 v[164:167], v148 offset:3072
	v_add_u32_e32 v148, s9, v145
	ds_read_b128 v[168:171], v148
	ds_read_b128 v[172:175], v148 offset:1024
	ds_read_b128 v[176:179], v148 offset:2048
	ds_read_b128 v[180:183], v148 offset:3072
	v_lshl_add_u64 v[148:149], s[96:97], 0, v[136:137]
	s_add_i32 m0, s46, 0xc000
	ds_read_b128 v[184:187], v147
	ds_read_b128 v[188:191], v147 offset:1024
	ds_read_b128 v[192:195], v147 offset:2048
	ds_read_b128 v[196:199], v147 offset:3072
	ds_read_b128 v[200:203], v147 offset:4096
	ds_read_b128 v[204:207], v147 offset:5120
	ds_read_b128 v[208:211], v147 offset:6144
	ds_read_b128 v[212:215], v147 offset:7168
	global_load_lds_dwordx4 v[148:149], off
	s_add_i32 m0, s46, 0xe000
	v_lshl_add_u64 v[148:149], s[96:97], 0, v[138:139]
	global_load_lds_dwordx4 v[148:149], off
	s_waitcnt vmcnt(8)
	s_waitcnt lgkmcnt(0)
	s_setprio 1
	s_barrier
	v_mfma_f32_16x16x32_bf16 v[126:129], v[140:143], v[184:187], v[126:129]
	v_mfma_f32_16x16x32_bf16 v[118:121], v[160:163], v[184:187], v[118:121]
	v_mfma_f32_16x16x32_bf16 v[110:113], v[140:143], v[192:195], v[110:113]
	v_mfma_f32_16x16x32_bf16 v[102:105], v[160:163], v[192:195], v[102:105]
	v_mfma_f32_16x16x32_bf16 v[94:97], v[140:143], v[200:203], v[94:97]
	v_mfma_f32_16x16x32_bf16 v[86:89], v[160:163], v[200:203], v[86:89]
	v_mfma_f32_16x16x32_bf16 v[78:81], v[140:143], v[208:211], v[78:81]
	v_mfma_f32_16x16x32_bf16 v[70:73], v[160:163], v[208:211], v[70:73]
	v_mfma_f32_16x16x32_bf16 v[126:129], v[156:159], v[188:191], v[126:129]
	v_mfma_f32_16x16x32_bf16 v[118:121], v[164:167], v[188:191], v[118:121]
	v_mfma_f32_16x16x32_bf16 v[110:113], v[156:159], v[196:199], v[110:113]
	v_mfma_f32_16x16x32_bf16 v[102:105], v[164:167], v[196:199], v[102:105]
	v_mfma_f32_16x16x32_bf16 v[94:97], v[156:159], v[204:207], v[94:97]
	v_mfma_f32_16x16x32_bf16 v[86:89], v[164:167], v[204:207], v[86:89]
	v_mfma_f32_16x16x32_bf16 v[78:81], v[156:159], v[212:215], v[78:81]
	v_mfma_f32_16x16x32_bf16 v[70:73], v[164:167], v[212:215], v[70:73]
	v_mfma_f32_16x16x32_bf16 v[122:125], v[168:171], v[184:187], v[122:125]
	v_mfma_f32_16x16x32_bf16 v[114:117], v[176:179], v[184:187], v[114:117]
	v_mfma_f32_16x16x32_bf16 v[106:109], v[168:171], v[192:195], v[106:109]
	v_mfma_f32_16x16x32_bf16 v[98:101], v[176:179], v[192:195], v[98:101]
	v_mfma_f32_16x16x32_bf16 v[90:93], v[168:171], v[200:203], v[90:93]
	v_mfma_f32_16x16x32_bf16 v[82:85], v[176:179], v[200:203], v[82:85]
	v_mfma_f32_16x16x32_bf16 v[74:77], v[168:171], v[208:211], v[74:77]
	v_mfma_f32_16x16x32_bf16 v[66:69], v[176:179], v[208:211], v[66:69]
	v_mfma_f32_16x16x32_bf16 v[122:125], v[172:175], v[188:191], v[122:125]
	v_mfma_f32_16x16x32_bf16 v[114:117], v[180:183], v[188:191], v[114:117]
	v_mfma_f32_16x16x32_bf16 v[106:109], v[172:175], v[196:199], v[106:109]
	v_mfma_f32_16x16x32_bf16 v[98:101], v[180:183], v[196:199], v[98:101]
	v_mfma_f32_16x16x32_bf16 v[90:93], v[172:175], v[204:207], v[90:93]
	v_mfma_f32_16x16x32_bf16 v[82:85], v[180:183], v[204:207], v[82:85]
	v_mfma_f32_16x16x32_bf16 v[74:77], v[172:175], v[212:215], v[74:77]
	v_mfma_f32_16x16x32_bf16 v[66:69], v[180:183], v[212:215], v[66:69]
	s_setprio 0
	s_barrier
	s_add_i32 s78, s78, s45
	v_lshl_add_u64 v[148:149], s[38:39], 0, v[0:1]
	s_mov_b32 m0, s78
	ds_read_b128 v[184:187], v147 offset:16384
	ds_read_b128 v[188:191], v147 offset:17408
	ds_read_b128 v[192:195], v147 offset:18432
	ds_read_b128 v[196:199], v147 offset:19456
	ds_read_b128 v[200:203], v147 offset:20480
	ds_read_b128 v[204:207], v147 offset:21504
	ds_read_b128 v[208:211], v147 offset:22528
	ds_read_b128 v[212:215], v147 offset:23552
	global_load_lds_dwordx4 v[148:149], off
	s_add_i32 m0, s78, 0x2000
	s_add_u32 s78, s38, 0x40000
	v_lshl_add_u64 v[150:151], s[38:39], 0, v[134:135]
	s_addc_u32 s79, s39, 0
	s_add_i32 s9, s9, s45
	global_load_lds_dwordx4 v[150:151], off
	v_lshl_add_u64 v[216:217], s[78:79], 0, v[0:1]
	s_mov_b32 m0, s9
	v_lshl_add_u64 v[218:219], vcc, 0, v[132:133]
	global_load_lds_dwordx4 v[216:217], off
	s_add_i32 m0, s9, 0x2000
	v_lshl_add_u64 v[216:217], s[78:79], 0, v[134:135]
	global_load_lds_dwordx4 v[216:217], off
	s_mov_b32 m0, s46
	v_lshl_add_u64 v[216:217], vcc, 0, v[130:131]
	global_load_lds_dwordx4 v[216:217], off
	s_mov_b32 m0, s47
	s_nop 0
	global_load_lds_dwordx4 v[218:219], off
	s_waitcnt vmcnt(8)
	s_waitcnt lgkmcnt(0)
	s_setprio 1
	s_barrier
	v_mfma_f32_16x16x32_bf16 v[62:65], v[140:143], v[184:187], v[62:65]
	v_mfma_f32_16x16x32_bf16 v[54:57], v[160:163], v[184:187], v[54:57]
	v_mfma_f32_16x16x32_bf16 v[46:49], v[140:143], v[192:195], v[46:49]
	v_mfma_f32_16x16x32_bf16 v[38:41], v[160:163], v[192:195], v[38:41]
	v_mfma_f32_16x16x32_bf16 v[30:33], v[140:143], v[200:203], v[30:33]
	v_mfma_f32_16x16x32_bf16 v[22:25], v[160:163], v[200:203], v[22:25]
	v_mfma_f32_16x16x32_bf16 v[14:17], v[140:143], v[208:211], v[14:17]
	v_mfma_f32_16x16x32_bf16 v[6:9], v[160:163], v[208:211], v[6:9]
	v_mfma_f32_16x16x32_bf16 v[62:65], v[156:159], v[188:191], v[62:65]
	v_mfma_f32_16x16x32_bf16 v[54:57], v[164:167], v[188:191], v[54:57]
	v_mfma_f32_16x16x32_bf16 v[46:49], v[156:159], v[196:199], v[46:49]
	v_mfma_f32_16x16x32_bf16 v[38:41], v[164:167], v[196:199], v[38:41]
	v_mfma_f32_16x16x32_bf16 v[30:33], v[156:159], v[204:207], v[30:33]
	v_mfma_f32_16x16x32_bf16 v[22:25], v[164:167], v[204:207], v[22:25]
	v_mfma_f32_16x16x32_bf16 v[14:17], v[156:159], v[212:215], v[14:17]
	v_mfma_f32_16x16x32_bf16 v[6:9], v[164:167], v[212:215], v[6:9]
	v_mfma_f32_16x16x32_bf16 v[58:61], v[168:171], v[184:187], v[58:61]
	v_mfma_f32_16x16x32_bf16 v[50:53], v[176:179], v[184:187], v[50:53]
	v_mfma_f32_16x16x32_bf16 v[42:45], v[168:171], v[192:195], v[42:45]
	v_mfma_f32_16x16x32_bf16 v[34:37], v[176:179], v[192:195], v[34:37]
	v_mfma_f32_16x16x32_bf16 v[26:29], v[168:171], v[200:203], v[26:29]
	v_mfma_f32_16x16x32_bf16 v[18:21], v[176:179], v[200:203], v[18:21]
	v_mfma_f32_16x16x32_bf16 v[10:13], v[168:171], v[208:211], v[10:13]
	v_mfma_f32_16x16x32_bf16 v[2:5], v[176:179], v[208:211], v[2:5]
	v_mfma_f32_16x16x32_bf16 v[58:61], v[172:175], v[188:191], v[58:61]
	v_mfma_f32_16x16x32_bf16 v[50:53], v[180:183], v[188:191], v[50:53]
	v_mfma_f32_16x16x32_bf16 v[42:45], v[172:175], v[196:199], v[42:45]
	v_mfma_f32_16x16x32_bf16 v[34:37], v[180:183], v[196:199], v[34:37]
	v_mfma_f32_16x16x32_bf16 v[26:29], v[172:175], v[204:207], v[26:29]
	v_mfma_f32_16x16x32_bf16 v[18:21], v[180:183], v[204:207], v[18:21]
	v_mfma_f32_16x16x32_bf16 v[10:13], v[172:175], v[212:215], v[10:13]
	v_mfma_f32_16x16x32_bf16 v[2:5], v[180:183], v[212:215], v[2:5]
	s_setprio 0
	s_barrier
	s_add_i32 s9, 0, 0x18000
	s_add_i32 s83, 0, 0x1c000
	v_add_u32_e32 v164, s9, v145
	v_add_u32_e32 v180, s83, v145
	ds_read_b128 v[140:143], v164
	ds_read_b128 v[156:159], v164 offset:1024
	ds_read_b128 v[160:163], v164 offset:2048
	ds_read_b128 v[164:167], v164 offset:3072
	ds_read_b128 v[168:171], v180
	ds_read_b128 v[172:175], v180 offset:1024
	ds_read_b128 v[176:179], v180 offset:2048
	ds_read_b128 v[180:183], v180 offset:3072
	s_add_u32 s78, vcc_lo, 0x40000
	s_addc_u32 s79, vcc_hi, 0
	s_mov_b32 m0, s48
	v_lshl_add_u64 v[220:221], s[78:79], 0, v[130:131]
	ds_read_b128 v[184:187], v147 offset:32768
	ds_read_b128 v[188:191], v147 offset:33792
	ds_read_b128 v[192:195], v147 offset:34816
	ds_read_b128 v[196:199], v147 offset:35840
	ds_read_b128 v[200:203], v147 offset:36864
	ds_read_b128 v[204:207], v147 offset:37888
	ds_read_b128 v[208:211], v147 offset:38912
	ds_read_b128 v[212:215], v147 offset:39936
	global_load_lds_dwordx4 v[220:221], off
	s_mov_b32 m0, s49
	v_lshl_add_u64 v[220:221], s[78:79], 0, v[132:133]
	global_load_lds_dwordx4 v[220:221], off
	s_waitcnt vmcnt(8)
	s_waitcnt lgkmcnt(0)
	s_setprio 1
	s_barrier
	v_mfma_f32_16x16x32_bf16 v[126:129], v[140:143], v[184:187], v[126:129]
	v_mfma_f32_16x16x32_bf16 v[118:121], v[160:163], v[184:187], v[118:121]
	v_mfma_f32_16x16x32_bf16 v[110:113], v[140:143], v[192:195], v[110:113]
	v_mfma_f32_16x16x32_bf16 v[102:105], v[160:163], v[192:195], v[102:105]
	v_mfma_f32_16x16x32_bf16 v[94:97], v[140:143], v[200:203], v[94:97]
	v_mfma_f32_16x16x32_bf16 v[86:89], v[160:163], v[200:203], v[86:89]
	v_mfma_f32_16x16x32_bf16 v[78:81], v[140:143], v[208:211], v[78:81]
	v_mfma_f32_16x16x32_bf16 v[70:73], v[160:163], v[208:211], v[70:73]
	v_mfma_f32_16x16x32_bf16 v[126:129], v[156:159], v[188:191], v[126:129]
	v_mfma_f32_16x16x32_bf16 v[118:121], v[164:167], v[188:191], v[118:121]
	v_mfma_f32_16x16x32_bf16 v[110:113], v[156:159], v[196:199], v[110:113]
	v_mfma_f32_16x16x32_bf16 v[102:105], v[164:167], v[196:199], v[102:105]
	v_mfma_f32_16x16x32_bf16 v[94:97], v[156:159], v[204:207], v[94:97]
	v_mfma_f32_16x16x32_bf16 v[86:89], v[164:167], v[204:207], v[86:89]
	v_mfma_f32_16x16x32_bf16 v[78:81], v[156:159], v[212:215], v[78:81]
	v_mfma_f32_16x16x32_bf16 v[70:73], v[164:167], v[212:215], v[70:73]
	v_mfma_f32_16x16x32_bf16 v[122:125], v[168:171], v[184:187], v[122:125]
	v_mfma_f32_16x16x32_bf16 v[114:117], v[176:179], v[184:187], v[114:117]
	v_mfma_f32_16x16x32_bf16 v[106:109], v[168:171], v[192:195], v[106:109]
	v_mfma_f32_16x16x32_bf16 v[98:101], v[176:179], v[192:195], v[98:101]
	v_mfma_f32_16x16x32_bf16 v[90:93], v[168:171], v[200:203], v[90:93]
	v_mfma_f32_16x16x32_bf16 v[82:85], v[176:179], v[200:203], v[82:85]
	v_mfma_f32_16x16x32_bf16 v[74:77], v[168:171], v[208:211], v[74:77]
	v_mfma_f32_16x16x32_bf16 v[66:69], v[176:179], v[208:211], v[66:69]
	v_mfma_f32_16x16x32_bf16 v[122:125], v[172:175], v[188:191], v[122:125]
	v_mfma_f32_16x16x32_bf16 v[114:117], v[180:183], v[188:191], v[114:117]
	v_mfma_f32_16x16x32_bf16 v[106:109], v[172:175], v[196:199], v[106:109]
	v_mfma_f32_16x16x32_bf16 v[98:101], v[180:183], v[196:199], v[98:101]
	v_mfma_f32_16x16x32_bf16 v[90:93], v[172:175], v[204:207], v[90:93]
	v_mfma_f32_16x16x32_bf16 v[82:85], v[180:183], v[204:207], v[82:85]
	v_mfma_f32_16x16x32_bf16 v[74:77], v[172:175], v[212:215], v[74:77]
	v_mfma_f32_16x16x32_bf16 v[66:69], v[180:183], v[212:215], v[66:69]
	s_setprio 0
	s_barrier
	s_add_i32 s9, s9, s45
	v_lshl_add_u64 v[148:149], v[148:149], 0, s[70:71]
	s_mov_b32 m0, s9
	ds_read_b128 v[184:187], v147 offset:49152
	ds_read_b128 v[188:191], v147 offset:50176
	ds_read_b128 v[192:195], v147 offset:51200
	ds_read_b128 v[196:199], v147 offset:52224
	ds_read_b128 v[200:203], v147 offset:53248
	ds_read_b128 v[204:207], v147 offset:54272
	ds_read_b128 v[208:211], v147 offset:55296
	ds_read_b128 v[212:215], v147 offset:56320
	global_load_lds_dwordx4 v[148:149], off
	s_add_i32 m0, s9, 0x2000
	s_add_u32 s38, s38, 0x40080
	v_lshl_add_u64 v[148:149], v[150:151], 0, s[70:71]
	s_addc_u32 s39, s39, 0
	s_add_i32 s9, s83, s45
	global_load_lds_dwordx4 v[148:149], off
	s_mov_b32 m0, s9
	v_lshl_add_u64 v[148:149], s[38:39], 0, v[0:1]
	global_load_lds_dwordx4 v[148:149], off
	s_add_i32 m0, s9, 0x2000
	v_lshl_add_u64 v[148:149], s[38:39], 0, v[134:135]
	global_load_lds_dwordx4 v[148:149], off
	s_mov_b32 m0, s50
	v_lshl_add_u64 v[148:149], v[216:217], 0, s[70:71]
	global_load_lds_dwordx4 v[148:149], off
	s_mov_b32 m0, s51
	v_lshl_add_u64 v[148:149], v[218:219], 0, s[70:71]
	global_load_lds_dwordx4 v[148:149], off
	s_waitcnt vmcnt(8)
	s_waitcnt lgkmcnt(0)
	s_setprio 1
	s_barrier
	v_mfma_f32_16x16x32_bf16 v[62:65], v[140:143], v[184:187], v[62:65]
	v_mfma_f32_16x16x32_bf16 v[54:57], v[160:163], v[184:187], v[54:57]
	v_mfma_f32_16x16x32_bf16 v[46:49], v[140:143], v[192:195], v[46:49]
	v_mfma_f32_16x16x32_bf16 v[38:41], v[160:163], v[192:195], v[38:41]
	v_mfma_f32_16x16x32_bf16 v[30:33], v[140:143], v[200:203], v[30:33]
	v_mfma_f32_16x16x32_bf16 v[22:25], v[160:163], v[200:203], v[22:25]
	v_mfma_f32_16x16x32_bf16 v[14:17], v[140:143], v[208:211], v[14:17]
	v_mfma_f32_16x16x32_bf16 v[6:9], v[160:163], v[208:211], v[6:9]
	v_mfma_f32_16x16x32_bf16 v[62:65], v[156:159], v[188:191], v[62:65]
	v_mfma_f32_16x16x32_bf16 v[54:57], v[164:167], v[188:191], v[54:57]
	v_mfma_f32_16x16x32_bf16 v[46:49], v[156:159], v[196:199], v[46:49]
	v_mfma_f32_16x16x32_bf16 v[38:41], v[164:167], v[196:199], v[38:41]
	v_mfma_f32_16x16x32_bf16 v[30:33], v[156:159], v[204:207], v[30:33]
	v_mfma_f32_16x16x32_bf16 v[22:25], v[164:167], v[204:207], v[22:25]
	v_mfma_f32_16x16x32_bf16 v[14:17], v[156:159], v[212:215], v[14:17]
	v_mfma_f32_16x16x32_bf16 v[6:9], v[164:167], v[212:215], v[6:9]
	v_mfma_f32_16x16x32_bf16 v[58:61], v[168:171], v[184:187], v[58:61]
	v_mfma_f32_16x16x32_bf16 v[50:53], v[176:179], v[184:187], v[50:53]
	v_mfma_f32_16x16x32_bf16 v[42:45], v[168:171], v[192:195], v[42:45]
	v_mfma_f32_16x16x32_bf16 v[34:37], v[176:179], v[192:195], v[34:37]
	v_mfma_f32_16x16x32_bf16 v[26:29], v[168:171], v[200:203], v[26:29]
	v_mfma_f32_16x16x32_bf16 v[18:21], v[176:179], v[200:203], v[18:21]
	v_mfma_f32_16x16x32_bf16 v[10:13], v[168:171], v[208:211], v[10:13]
	v_mfma_f32_16x16x32_bf16 v[2:5], v[176:179], v[208:211], v[2:5]
	v_mfma_f32_16x16x32_bf16 v[58:61], v[172:175], v[188:191], v[58:61]
	v_mfma_f32_16x16x32_bf16 v[50:53], v[180:183], v[188:191], v[50:53]
	v_mfma_f32_16x16x32_bf16 v[42:45], v[172:175], v[196:199], v[42:45]
	v_mfma_f32_16x16x32_bf16 v[34:37], v[180:183], v[196:199], v[34:37]
	v_mfma_f32_16x16x32_bf16 v[26:29], v[172:175], v[204:207], v[26:29]
	v_mfma_f32_16x16x32_bf16 v[18:21], v[180:183], v[204:207], v[18:21]
	v_mfma_f32_16x16x32_bf16 v[10:13], v[172:175], v[212:215], v[10:13]
	v_mfma_f32_16x16x32_bf16 v[2:5], v[180:183], v[212:215], v[2:5]
	s_setprio 0
	s_barrier
	s_add_i32 s75, s75, 2
	s_add_u32 s96, s96, 0x100
	s_addc_u32 s97, s97, 0
	s_add_u32 s53, s53, 0x100
	s_addc_u32 s61, s61, 0
	s_cmp_gt_u32 s75, 13
	s_cbranch_scc0 .LBB0_846
	s_and_b64 vcc, exec, s[14:15]
	s_cbranch_vccz .LBB0_849
	s_barrier

.LBB0_950:
	s_add_i32 s9, s26, 2
	s_add_u32 s60, s38, 0x100
	s_addc_u32 s61, s39, 0
	s_add_i32 s78, 0, 0x10000
	s_cmp_eq_u32 s29, s26
	s_cselect_b32 s73, s25, s61
	s_cselect_b32 s72, s24, s60
	s_cselect_b32 s27, s37, vcc_hi
	s_cselect_b32 s26, s36, vcc_lo
	s_add_i32 s79, 0, 0x14000
	v_add_u32_e32 v156, s78, v177
	v_add_u32_e32 v172, s79, v177
	ds_read_b128 v[140:143], v156
	ds_read_b128 v[144:147], v156 offset:1024
	ds_read_b128 v[148:151], v156 offset:2048
	ds_read_b128 v[156:159], v156 offset:3072
	ds_read_b128 v[160:163], v172
	ds_read_b128 v[164:167], v172 offset:1024
	ds_read_b128 v[168:171], v172 offset:2048
	ds_read_b128 v[172:175], v172 offset:3072
	v_lshl_add_u64 v[212:213], s[38:39], 0, v[136:137]
	s_add_i32 m0, s50, 0xc000
	ds_read_b128 v[180:183], v179
	ds_read_b128 v[184:187], v179 offset:1024
	ds_read_b128 v[188:191], v179 offset:2048
	ds_read_b128 v[192:195], v179 offset:3072
	ds_read_b128 v[196:199], v179 offset:4096
	ds_read_b128 v[200:203], v179 offset:5120
	ds_read_b128 v[204:207], v179 offset:6144
	ds_read_b128 v[208:211], v179 offset:7168
	global_load_lds_dwordx4 v[212:213], off
	s_add_i32 m0, s50, 0xe000
	v_lshl_add_u64 v[212:213], s[38:39], 0, v[138:139]
	global_load_lds_dwordx4 v[212:213], off
	s_waitcnt vmcnt(8)
	s_waitcnt lgkmcnt(0)
	s_setprio 1
	s_barrier
	v_mfma_f32_16x16x32_bf16 v[126:129], v[140:143], v[180:183], v[126:129]
	v_mfma_f32_16x16x32_bf16 v[122:125], v[148:151], v[180:183], v[122:125]
	v_mfma_f32_16x16x32_bf16 v[110:113], v[140:143], v[188:191], v[110:113]
	v_mfma_f32_16x16x32_bf16 v[106:109], v[148:151], v[188:191], v[106:109]
	v_mfma_f32_16x16x32_bf16 v[94:97], v[140:143], v[196:199], v[94:97]
	v_mfma_f32_16x16x32_bf16 v[90:93], v[148:151], v[196:199], v[90:93]
	v_mfma_f32_16x16x32_bf16 v[78:81], v[140:143], v[204:207], v[78:81]
	v_mfma_f32_16x16x32_bf16 v[74:77], v[148:151], v[204:207], v[74:77]
	v_mfma_f32_16x16x32_bf16 v[126:129], v[144:147], v[184:187], v[126:129]
	v_mfma_f32_16x16x32_bf16 v[122:125], v[156:159], v[184:187], v[122:125]
	v_mfma_f32_16x16x32_bf16 v[110:113], v[144:147], v[192:195], v[110:113]
	v_mfma_f32_16x16x32_bf16 v[106:109], v[156:159], v[192:195], v[106:109]
	v_mfma_f32_16x16x32_bf16 v[94:97], v[144:147], v[200:203], v[94:97]
	v_mfma_f32_16x16x32_bf16 v[90:93], v[156:159], v[200:203], v[90:93]
	v_mfma_f32_16x16x32_bf16 v[78:81], v[144:147], v[208:211], v[78:81]
	v_mfma_f32_16x16x32_bf16 v[74:77], v[156:159], v[208:211], v[74:77]
	v_mfma_f32_16x16x32_bf16 v[118:121], v[160:163], v[180:183], v[118:121]
	v_mfma_f32_16x16x32_bf16 v[114:117], v[168:171], v[180:183], v[114:117]
	v_mfma_f32_16x16x32_bf16 v[102:105], v[160:163], v[188:191], v[102:105]
	v_mfma_f32_16x16x32_bf16 v[98:101], v[168:171], v[188:191], v[98:101]
	v_mfma_f32_16x16x32_bf16 v[86:89], v[160:163], v[196:199], v[86:89]
	v_mfma_f32_16x16x32_bf16 v[82:85], v[168:171], v[196:199], v[82:85]
	v_mfma_f32_16x16x32_bf16 v[70:73], v[160:163], v[204:207], v[70:73]
	v_mfma_f32_16x16x32_bf16 v[66:69], v[168:171], v[204:207], v[66:69]
	v_mfma_f32_16x16x32_bf16 v[118:121], v[164:167], v[184:187], v[118:121]
	v_mfma_f32_16x16x32_bf16 v[114:117], v[172:175], v[184:187], v[114:117]
	v_mfma_f32_16x16x32_bf16 v[102:105], v[164:167], v[192:195], v[102:105]
	v_mfma_f32_16x16x32_bf16 v[98:101], v[172:175], v[192:195], v[98:101]
	v_mfma_f32_16x16x32_bf16 v[86:89], v[164:167], v[200:203], v[86:89]
	v_mfma_f32_16x16x32_bf16 v[82:85], v[172:175], v[200:203], v[82:85]
	v_mfma_f32_16x16x32_bf16 v[70:73], v[164:167], v[208:211], v[70:73]
	v_mfma_f32_16x16x32_bf16 v[66:69], v[172:175], v[208:211], v[66:69]
	s_setprio 0
	s_barrier
	s_add_i32 s38, s78, s49
	v_lshl_add_u64 v[212:213], s[26:27], 0, v[0:1]
	s_mov_b32 m0, s38
	ds_read_b128 v[180:183], v179 offset:16384
	ds_read_b128 v[184:187], v179 offset:17408
	ds_read_b128 v[188:191], v179 offset:18432
	ds_read_b128 v[192:195], v179 offset:19456
	ds_read_b128 v[196:199], v179 offset:20480
	ds_read_b128 v[200:203], v179 offset:21504
	ds_read_b128 v[204:207], v179 offset:22528
	ds_read_b128 v[208:211], v179 offset:23552
	global_load_lds_dwordx4 v[212:213], off
	s_add_i32 m0, s38, 0x2000
	s_add_u32 s38, s26, 0xb0000
	v_lshl_add_u64 v[214:215], s[26:27], 0, v[134:135]
	s_addc_u32 s39, s27, 0
	s_add_i32 s78, s79, s49
	global_load_lds_dwordx4 v[214:215], off
	v_lshl_add_u64 v[216:217], s[38:39], 0, v[0:1]
	s_mov_b32 m0, s78
	v_lshl_add_u64 v[218:219], s[72:73], 0, v[132:133]
	global_load_lds_dwordx4 v[216:217], off
	s_add_i32 m0, s78, 0x2000
	v_lshl_add_u64 v[216:217], s[38:39], 0, v[134:135]
	global_load_lds_dwordx4 v[216:217], off
	s_mov_b32 m0, s50
	v_lshl_add_u64 v[216:217], s[72:73], 0, v[130:131]
	global_load_lds_dwordx4 v[216:217], off
	s_mov_b32 m0, s51
	s_nop 0
	global_load_lds_dwordx4 v[218:219], off
	s_waitcnt vmcnt(8)
	s_waitcnt lgkmcnt(0)
	s_setprio 1
	s_barrier
	v_mfma_f32_16x16x32_bf16 v[62:65], v[140:143], v[180:183], v[62:65]
	v_mfma_f32_16x16x32_bf16 v[58:61], v[148:151], v[180:183], v[58:61]
	v_mfma_f32_16x16x32_bf16 v[46:49], v[140:143], v[188:191], v[46:49]
	v_mfma_f32_16x16x32_bf16 v[42:45], v[148:151], v[188:191], v[42:45]
	v_mfma_f32_16x16x32_bf16 v[30:33], v[140:143], v[196:199], v[30:33]
	v_mfma_f32_16x16x32_bf16 v[26:29], v[148:151], v[196:199], v[26:29]
	v_mfma_f32_16x16x32_bf16 v[14:17], v[140:143], v[204:207], v[14:17]
	v_mfma_f32_16x16x32_bf16 v[10:13], v[148:151], v[204:207], v[10:13]
	v_mfma_f32_16x16x32_bf16 v[62:65], v[144:147], v[184:187], v[62:65]
	v_mfma_f32_16x16x32_bf16 v[58:61], v[156:159], v[184:187], v[58:61]
	v_mfma_f32_16x16x32_bf16 v[46:49], v[144:147], v[192:195], v[46:49]
	v_mfma_f32_16x16x32_bf16 v[42:45], v[156:159], v[192:195], v[42:45]
	v_mfma_f32_16x16x32_bf16 v[30:33], v[144:147], v[200:203], v[30:33]
	v_mfma_f32_16x16x32_bf16 v[26:29], v[156:159], v[200:203], v[26:29]
	v_mfma_f32_16x16x32_bf16 v[14:17], v[144:147], v[208:211], v[14:17]
	v_mfma_f32_16x16x32_bf16 v[10:13], v[156:159], v[208:211], v[10:13]
	v_mfma_f32_16x16x32_bf16 v[54:57], v[160:163], v[180:183], v[54:57]
	v_mfma_f32_16x16x32_bf16 v[50:53], v[168:171], v[180:183], v[50:53]
	v_mfma_f32_16x16x32_bf16 v[38:41], v[160:163], v[188:191], v[38:41]
	v_mfma_f32_16x16x32_bf16 v[34:37], v[168:171], v[188:191], v[34:37]
	v_mfma_f32_16x16x32_bf16 v[22:25], v[160:163], v[196:199], v[22:25]
	v_mfma_f32_16x16x32_bf16 v[18:21], v[168:171], v[196:199], v[18:21]
	v_mfma_f32_16x16x32_bf16 v[6:9], v[160:163], v[204:207], v[6:9]
	v_mfma_f32_16x16x32_bf16 v[2:5], v[168:171], v[204:207], v[2:5]
	v_mfma_f32_16x16x32_bf16 v[54:57], v[164:167], v[184:187], v[54:57]
	v_mfma_f32_16x16x32_bf16 v[50:53], v[172:175], v[184:187], v[50:53]
	v_mfma_f32_16x16x32_bf16 v[38:41], v[164:167], v[192:195], v[38:41]
	v_mfma_f32_16x16x32_bf16 v[34:37], v[172:175], v[192:195], v[34:37]
	v_mfma_f32_16x16x32_bf16 v[22:25], v[164:167], v[200:203], v[22:25]
	v_mfma_f32_16x16x32_bf16 v[18:21], v[172:175], v[200:203], v[18:21]
	v_mfma_f32_16x16x32_bf16 v[6:9], v[164:167], v[208:211], v[6:9]
	v_mfma_f32_16x16x32_bf16 v[2:5], v[172:175], v[208:211], v[2:5]
	s_setprio 0
	s_barrier
	s_add_i32 s78, 0, 0x18000
	s_add_i32 s79, 0, 0x1c000
	v_add_u32_e32 v156, s78, v177
	v_add_u32_e32 v172, s79, v177
	ds_read_b128 v[140:143], v156
	ds_read_b128 v[144:147], v156 offset:1024
	ds_read_b128 v[148:151], v156 offset:2048
	ds_read_b128 v[156:159], v156 offset:3072
	ds_read_b128 v[160:163], v172
	ds_read_b128 v[164:167], v172 offset:1024
	ds_read_b128 v[168:171], v172 offset:2048
	ds_read_b128 v[172:175], v172 offset:3072
	s_add_u32 s38, s72, 0xb0000
	s_addc_u32 s39, s73, 0
	s_mov_b32 m0, s52
	v_lshl_add_u64 v[220:221], s[38:39], 0, v[130:131]
	ds_read_b128 v[180:183], v179 offset:32768
	ds_read_b128 v[184:187], v179 offset:33792
	ds_read_b128 v[188:191], v179 offset:34816
	ds_read_b128 v[192:195], v179 offset:35840
	ds_read_b128 v[196:199], v179 offset:36864
	ds_read_b128 v[200:203], v179 offset:37888
	ds_read_b128 v[204:207], v179 offset:38912
	ds_read_b128 v[208:211], v179 offset:39936
	global_load_lds_dwordx4 v[220:221], off
	s_mov_b32 m0, s53
	v_lshl_add_u64 v[220:221], s[38:39], 0, v[132:133]
	global_load_lds_dwordx4 v[220:221], off
	s_waitcnt vmcnt(8)
	s_waitcnt lgkmcnt(0)
	s_setprio 1
	s_barrier
	v_mfma_f32_16x16x32_bf16 v[126:129], v[140:143], v[180:183], v[126:129]
	v_mfma_f32_16x16x32_bf16 v[122:125], v[148:151], v[180:183], v[122:125]
	v_mfma_f32_16x16x32_bf16 v[110:113], v[140:143], v[188:191], v[110:113]
	v_mfma_f32_16x16x32_bf16 v[106:109], v[148:151], v[188:191], v[106:109]
	v_mfma_f32_16x16x32_bf16 v[94:97], v[140:143], v[196:199], v[94:97]
	v_mfma_f32_16x16x32_bf16 v[90:93], v[148:151], v[196:199], v[90:93]
	v_mfma_f32_16x16x32_bf16 v[78:81], v[140:143], v[204:207], v[78:81]
	v_mfma_f32_16x16x32_bf16 v[74:77], v[148:151], v[204:207], v[74:77]
	v_mfma_f32_16x16x32_bf16 v[126:129], v[144:147], v[184:187], v[126:129]
	v_mfma_f32_16x16x32_bf16 v[122:125], v[156:159], v[184:187], v[122:125]
	v_mfma_f32_16x16x32_bf16 v[110:113], v[144:147], v[192:195], v[110:113]
	v_mfma_f32_16x16x32_bf16 v[106:109], v[156:159], v[192:195], v[106:109]
	v_mfma_f32_16x16x32_bf16 v[94:97], v[144:147], v[200:203], v[94:97]
	v_mfma_f32_16x16x32_bf16 v[90:93], v[156:159], v[200:203], v[90:93]
	v_mfma_f32_16x16x32_bf16 v[78:81], v[144:147], v[208:211], v[78:81]
	v_mfma_f32_16x16x32_bf16 v[74:77], v[156:159], v[208:211], v[74:77]
	v_mfma_f32_16x16x32_bf16 v[118:121], v[160:163], v[180:183], v[118:121]
	v_mfma_f32_16x16x32_bf16 v[114:117], v[168:171], v[180:183], v[114:117]
	v_mfma_f32_16x16x32_bf16 v[102:105], v[160:163], v[188:191], v[102:105]
	v_mfma_f32_16x16x32_bf16 v[98:101], v[168:171], v[188:191], v[98:101]
	v_mfma_f32_16x16x32_bf16 v[86:89], v[160:163], v[196:199], v[86:89]
	v_mfma_f32_16x16x32_bf16 v[82:85], v[168:171], v[196:199], v[82:85]
	v_mfma_f32_16x16x32_bf16 v[70:73], v[160:163], v[204:207], v[70:73]
	v_mfma_f32_16x16x32_bf16 v[66:69], v[168:171], v[204:207], v[66:69]
	v_mfma_f32_16x16x32_bf16 v[118:121], v[164:167], v[184:187], v[118:121]
	v_mfma_f32_16x16x32_bf16 v[114:117], v[172:175], v[184:187], v[114:117]
	v_mfma_f32_16x16x32_bf16 v[102:105], v[164:167], v[192:195], v[102:105]
	v_mfma_f32_16x16x32_bf16 v[98:101], v[172:175], v[192:195], v[98:101]
	v_mfma_f32_16x16x32_bf16 v[86:89], v[164:167], v[200:203], v[86:89]
	v_mfma_f32_16x16x32_bf16 v[82:85], v[172:175], v[200:203], v[82:85]
	v_mfma_f32_16x16x32_bf16 v[70:73], v[164:167], v[208:211], v[70:73]
	v_mfma_f32_16x16x32_bf16 v[66:69], v[172:175], v[208:211], v[66:69]
	s_setprio 0
	s_barrier
	s_add_i32 s38, s78, s49
	v_lshl_add_u64 v[212:213], v[212:213], 0, s[70:71]
	s_mov_b32 m0, s38
	ds_read_b128 v[180:183], v179 offset:49152
	ds_read_b128 v[184:187], v179 offset:50176
	ds_read_b128 v[188:191], v179 offset:51200
	ds_read_b128 v[192:195], v179 offset:52224
	ds_read_b128 v[196:199], v179 offset:53248
	ds_read_b128 v[200:203], v179 offset:54272
	ds_read_b128 v[204:207], v179 offset:55296
	ds_read_b128 v[208:211], v179 offset:56320
	global_load_lds_dwordx4 v[212:213], off
	s_add_i32 m0, s38, 0x2000
	s_add_u32 s26, s26, 0xb0080
	v_lshl_add_u64 v[212:213], v[214:215], 0, s[70:71]
	s_addc_u32 s27, s27, 0
	s_add_i32 s38, s79, s49
	global_load_lds_dwordx4 v[212:213], off
	s_mov_b32 m0, s38
	v_lshl_add_u64 v[212:213], s[26:27], 0, v[0:1]
	global_load_lds_dwordx4 v[212:213], off
	s_add_i32 m0, s38, 0x2000
	v_lshl_add_u64 v[212:213], s[26:27], 0, v[134:135]
	global_load_lds_dwordx4 v[212:213], off
	s_mov_b32 m0, s74
	v_lshl_add_u64 v[212:213], v[216:217], 0, s[70:71]
	global_load_lds_dwordx4 v[212:213], off
	s_mov_b32 m0, s75
	v_lshl_add_u64 v[212:213], v[218:219], 0, s[70:71]
	global_load_lds_dwordx4 v[212:213], off
	s_waitcnt vmcnt(8)
	s_waitcnt lgkmcnt(0)
	s_setprio 1
	s_barrier
	v_mfma_f32_16x16x32_bf16 v[62:65], v[140:143], v[180:183], v[62:65]
	v_mfma_f32_16x16x32_bf16 v[58:61], v[148:151], v[180:183], v[58:61]
	v_mfma_f32_16x16x32_bf16 v[46:49], v[140:143], v[188:191], v[46:49]
	v_mfma_f32_16x16x32_bf16 v[42:45], v[148:151], v[188:191], v[42:45]
	v_mfma_f32_16x16x32_bf16 v[30:33], v[140:143], v[196:199], v[30:33]
	v_mfma_f32_16x16x32_bf16 v[26:29], v[148:151], v[196:199], v[26:29]
	v_mfma_f32_16x16x32_bf16 v[14:17], v[140:143], v[204:207], v[14:17]
	v_mfma_f32_16x16x32_bf16 v[10:13], v[148:151], v[204:207], v[10:13]
	v_mfma_f32_16x16x32_bf16 v[62:65], v[144:147], v[184:187], v[62:65]
	v_mfma_f32_16x16x32_bf16 v[58:61], v[156:159], v[184:187], v[58:61]
	v_mfma_f32_16x16x32_bf16 v[46:49], v[144:147], v[192:195], v[46:49]
	v_mfma_f32_16x16x32_bf16 v[42:45], v[156:159], v[192:195], v[42:45]
	v_mfma_f32_16x16x32_bf16 v[30:33], v[144:147], v[200:203], v[30:33]
	v_mfma_f32_16x16x32_bf16 v[26:29], v[156:159], v[200:203], v[26:29]
	v_mfma_f32_16x16x32_bf16 v[14:17], v[144:147], v[208:211], v[14:17]
	v_mfma_f32_16x16x32_bf16 v[10:13], v[156:159], v[208:211], v[10:13]
	v_mfma_f32_16x16x32_bf16 v[54:57], v[160:163], v[180:183], v[54:57]
	v_mfma_f32_16x16x32_bf16 v[50:53], v[168:171], v[180:183], v[50:53]
	v_mfma_f32_16x16x32_bf16 v[38:41], v[160:163], v[188:191], v[38:41]
	v_mfma_f32_16x16x32_bf16 v[34:37], v[168:171], v[188:191], v[34:37]
	v_mfma_f32_16x16x32_bf16 v[22:25], v[160:163], v[196:199], v[22:25]
	v_mfma_f32_16x16x32_bf16 v[18:21], v[168:171], v[196:199], v[18:21]
	v_mfma_f32_16x16x32_bf16 v[6:9], v[160:163], v[204:207], v[6:9]
	v_mfma_f32_16x16x32_bf16 v[2:5], v[168:171], v[204:207], v[2:5]
	v_mfma_f32_16x16x32_bf16 v[54:57], v[164:167], v[184:187], v[54:57]
	v_mfma_f32_16x16x32_bf16 v[50:53], v[172:175], v[184:187], v[50:53]
	v_mfma_f32_16x16x32_bf16 v[38:41], v[164:167], v[192:195], v[38:41]
	v_mfma_f32_16x16x32_bf16 v[34:37], v[172:175], v[192:195], v[34:37]
	v_mfma_f32_16x16x32_bf16 v[22:25], v[164:167], v[200:203], v[22:25]
	v_mfma_f32_16x16x32_bf16 v[18:21], v[172:175], v[200:203], v[18:21]
	v_mfma_f32_16x16x32_bf16 v[6:9], v[164:167], v[208:211], v[6:9]
	v_mfma_f32_16x16x32_bf16 v[2:5], v[172:175], v[208:211], v[2:5]
	s_setprio 0
	s_barrier
	s_add_u32 vcc_lo, vcc_lo, 0x100
	s_addc_u32 vcc_hi, vcc_hi, 0
	s_cmp_ge_u32 s9, s28
	s_mov_b64 s[38:39], s[60:61]
	s_mov_b32 s26, s9
	s_cbranch_scc0 .LBB0_950
	s_and_b64 vcc, exec, s[22:23]
	s_cbranch_vccz .LBB0_953

.LBB0_1000:
	s_add_i32 s9, s26, 2
	s_add_u32 s60, s38, 0x100
	s_addc_u32 s61, s39, 0
	s_add_i32 s78, 0, 0x10000
	s_cmp_eq_u32 s29, s26
	s_cselect_b32 s73, s25, s61
	s_cselect_b32 s72, s24, s60
	v_add_u32_e32 v148, s78, v251
	s_cselect_b32 s27, s37, vcc_hi
	s_cselect_b32 s26, s36, vcc_lo
	s_add_i32 s79, 0, 0x14000
	ds_read_b128 v[140:143], v148
	ds_read_b128 v[144:147], v148 offset:1024
	ds_read_b128 v[156:159], v148 offset:2048
	ds_read_b128 v[160:163], v148 offset:3072
	v_add_u32_e32 v148, s79, v251
	ds_read_b128 v[164:167], v148
	ds_read_b128 v[168:171], v148 offset:1024
	ds_read_b128 v[172:175], v148 offset:2048
	ds_read_b128 v[176:179], v148 offset:3072
	v_lshl_add_u64 v[148:149], s[38:39], 0, v[136:137]
	s_add_i32 m0, s50, 0xc000
	ds_read_b128 v[180:183], v253
	ds_read_b128 v[184:187], v253 offset:1024
	ds_read_b128 v[188:191], v253 offset:2048
	ds_read_b128 v[192:195], v253 offset:3072
	ds_read_b128 v[196:199], v253 offset:4096
	ds_read_b128 v[200:203], v253 offset:5120
	ds_read_b128 v[204:207], v253 offset:6144
	ds_read_b128 v[208:211], v253 offset:7168
	global_load_lds_dwordx4 v[148:149], off
	s_add_i32 m0, s50, 0xe000
	v_lshl_add_u64 v[148:149], s[38:39], 0, v[138:139]
	global_load_lds_dwordx4 v[148:149], off
	s_waitcnt vmcnt(8)
	s_waitcnt lgkmcnt(0)
	s_setprio 1
	s_barrier
	v_mfma_f32_16x16x32_bf16 v[126:129], v[140:143], v[180:183], v[126:129]
	v_mfma_f32_16x16x32_bf16 v[122:125], v[156:159], v[180:183], v[122:125]
	v_mfma_f32_16x16x32_bf16 v[110:113], v[140:143], v[188:191], v[110:113]
	v_mfma_f32_16x16x32_bf16 v[106:109], v[156:159], v[188:191], v[106:109]
	v_mfma_f32_16x16x32_bf16 v[94:97], v[140:143], v[196:199], v[94:97]
	v_mfma_f32_16x16x32_bf16 v[90:93], v[156:159], v[196:199], v[90:93]
	v_mfma_f32_16x16x32_bf16 v[78:81], v[140:143], v[204:207], v[78:81]
	v_mfma_f32_16x16x32_bf16 v[74:77], v[156:159], v[204:207], v[74:77]
	v_mfma_f32_16x16x32_bf16 v[126:129], v[144:147], v[184:187], v[126:129]
	v_mfma_f32_16x16x32_bf16 v[122:125], v[160:163], v[184:187], v[122:125]
	v_mfma_f32_16x16x32_bf16 v[110:113], v[144:147], v[192:195], v[110:113]
	v_mfma_f32_16x16x32_bf16 v[106:109], v[160:163], v[192:195], v[106:109]
	v_mfma_f32_16x16x32_bf16 v[94:97], v[144:147], v[200:203], v[94:97]
	v_mfma_f32_16x16x32_bf16 v[90:93], v[160:163], v[200:203], v[90:93]
	v_mfma_f32_16x16x32_bf16 v[78:81], v[144:147], v[208:211], v[78:81]
	v_mfma_f32_16x16x32_bf16 v[74:77], v[160:163], v[208:211], v[74:77]
	v_mfma_f32_16x16x32_bf16 v[118:121], v[164:167], v[180:183], v[118:121]
	v_mfma_f32_16x16x32_bf16 v[114:117], v[172:175], v[180:183], v[114:117]
	v_mfma_f32_16x16x32_bf16 v[102:105], v[164:167], v[188:191], v[102:105]
	v_mfma_f32_16x16x32_bf16 v[98:101], v[172:175], v[188:191], v[98:101]
	v_mfma_f32_16x16x32_bf16 v[86:89], v[164:167], v[196:199], v[86:89]
	v_mfma_f32_16x16x32_bf16 v[82:85], v[172:175], v[196:199], v[82:85]
	v_mfma_f32_16x16x32_bf16 v[70:73], v[164:167], v[204:207], v[70:73]
	v_mfma_f32_16x16x32_bf16 v[66:69], v[172:175], v[204:207], v[66:69]
	v_mfma_f32_16x16x32_bf16 v[118:121], v[168:171], v[184:187], v[118:121]
	v_mfma_f32_16x16x32_bf16 v[114:117], v[176:179], v[184:187], v[114:117]
	v_mfma_f32_16x16x32_bf16 v[102:105], v[168:171], v[192:195], v[102:105]
	v_mfma_f32_16x16x32_bf16 v[98:101], v[176:179], v[192:195], v[98:101]
	v_mfma_f32_16x16x32_bf16 v[86:89], v[168:171], v[200:203], v[86:89]
	v_mfma_f32_16x16x32_bf16 v[82:85], v[176:179], v[200:203], v[82:85]
	v_mfma_f32_16x16x32_bf16 v[70:73], v[168:171], v[208:211], v[70:73]
	v_mfma_f32_16x16x32_bf16 v[66:69], v[176:179], v[208:211], v[66:69]
	s_setprio 0
	s_barrier
	s_add_i32 s38, s78, s49
	v_lshl_add_u64 v[148:149], s[26:27], 0, v[0:1]
	s_mov_b32 m0, s38
	ds_read_b128 v[180:183], v253 offset:16384
	ds_read_b128 v[184:187], v253 offset:17408
	ds_read_b128 v[188:191], v253 offset:18432
	ds_read_b128 v[192:195], v253 offset:19456
	ds_read_b128 v[196:199], v253 offset:20480
	ds_read_b128 v[200:203], v253 offset:21504
	ds_read_b128 v[204:207], v253 offset:22528
	ds_read_b128 v[208:211], v253 offset:23552
	global_load_lds_dwordx4 v[148:149], off
	s_add_i32 m0, s38, 0x2000
	s_add_u32 s38, s26, 0xb0000
	v_lshl_add_u64 v[150:151], s[26:27], 0, v[134:135]
	s_addc_u32 s39, s27, 0
	s_add_i32 s78, s79, s49
	global_load_lds_dwordx4 v[150:151], off
	v_lshl_add_u64 v[212:213], s[38:39], 0, v[0:1]
	s_mov_b32 m0, s78
	v_lshl_add_u64 v[214:215], s[72:73], 0, v[132:133]
	global_load_lds_dwordx4 v[212:213], off
	s_add_i32 m0, s78, 0x2000
	v_lshl_add_u64 v[212:213], s[38:39], 0, v[134:135]
	global_load_lds_dwordx4 v[212:213], off
	s_mov_b32 m0, s50
	v_lshl_add_u64 v[212:213], s[72:73], 0, v[130:131]
	global_load_lds_dwordx4 v[212:213], off
	s_mov_b32 m0, s51
	s_nop 0
	global_load_lds_dwordx4 v[214:215], off
	s_waitcnt vmcnt(8)
	s_waitcnt lgkmcnt(0)
	s_setprio 1
	s_barrier
	v_mfma_f32_16x16x32_bf16 v[62:65], v[140:143], v[180:183], v[62:65]
	v_mfma_f32_16x16x32_bf16 v[58:61], v[156:159], v[180:183], v[58:61]
	v_mfma_f32_16x16x32_bf16 v[46:49], v[140:143], v[188:191], v[46:49]
	v_mfma_f32_16x16x32_bf16 v[42:45], v[156:159], v[188:191], v[42:45]
	v_mfma_f32_16x16x32_bf16 v[30:33], v[140:143], v[196:199], v[30:33]
	v_mfma_f32_16x16x32_bf16 v[26:29], v[156:159], v[196:199], v[26:29]
	v_mfma_f32_16x16x32_bf16 v[14:17], v[140:143], v[204:207], v[14:17]
	v_mfma_f32_16x16x32_bf16 v[10:13], v[156:159], v[204:207], v[10:13]
	v_mfma_f32_16x16x32_bf16 v[62:65], v[144:147], v[184:187], v[62:65]
	v_mfma_f32_16x16x32_bf16 v[58:61], v[160:163], v[184:187], v[58:61]
	v_mfma_f32_16x16x32_bf16 v[46:49], v[144:147], v[192:195], v[46:49]
	v_mfma_f32_16x16x32_bf16 v[42:45], v[160:163], v[192:195], v[42:45]
	v_mfma_f32_16x16x32_bf16 v[30:33], v[144:147], v[200:203], v[30:33]
	v_mfma_f32_16x16x32_bf16 v[26:29], v[160:163], v[200:203], v[26:29]
	v_mfma_f32_16x16x32_bf16 v[14:17], v[144:147], v[208:211], v[14:17]
	v_mfma_f32_16x16x32_bf16 v[10:13], v[160:163], v[208:211], v[10:13]
	v_mfma_f32_16x16x32_bf16 v[54:57], v[164:167], v[180:183], v[54:57]
	v_mfma_f32_16x16x32_bf16 v[50:53], v[172:175], v[180:183], v[50:53]
	v_mfma_f32_16x16x32_bf16 v[38:41], v[164:167], v[188:191], v[38:41]
	v_mfma_f32_16x16x32_bf16 v[34:37], v[172:175], v[188:191], v[34:37]
	v_mfma_f32_16x16x32_bf16 v[22:25], v[164:167], v[196:199], v[22:25]
	v_mfma_f32_16x16x32_bf16 v[18:21], v[172:175], v[196:199], v[18:21]
	v_mfma_f32_16x16x32_bf16 v[6:9], v[164:167], v[204:207], v[6:9]
	v_mfma_f32_16x16x32_bf16 v[2:5], v[172:175], v[204:207], v[2:5]
	v_mfma_f32_16x16x32_bf16 v[54:57], v[168:171], v[184:187], v[54:57]
	v_mfma_f32_16x16x32_bf16 v[50:53], v[176:179], v[184:187], v[50:53]
	v_mfma_f32_16x16x32_bf16 v[38:41], v[168:171], v[192:195], v[38:41]
	v_mfma_f32_16x16x32_bf16 v[34:37], v[176:179], v[192:195], v[34:37]
	v_mfma_f32_16x16x32_bf16 v[22:25], v[168:171], v[200:203], v[22:25]
	v_mfma_f32_16x16x32_bf16 v[18:21], v[176:179], v[200:203], v[18:21]
	v_mfma_f32_16x16x32_bf16 v[6:9], v[168:171], v[208:211], v[6:9]
	v_mfma_f32_16x16x32_bf16 v[2:5], v[176:179], v[208:211], v[2:5]
	s_setprio 0
	s_barrier
	s_add_i32 s78, 0, 0x18000
	s_add_i32 s79, 0, 0x1c000
	v_add_u32_e32 v160, s78, v251
	v_add_u32_e32 v176, s79, v251
	ds_read_b128 v[140:143], v160
	ds_read_b128 v[144:147], v160 offset:1024
	ds_read_b128 v[156:159], v160 offset:2048
	ds_read_b128 v[160:163], v160 offset:3072
	ds_read_b128 v[164:167], v176
	ds_read_b128 v[168:171], v176 offset:1024
	ds_read_b128 v[172:175], v176 offset:2048
	ds_read_b128 v[176:179], v176 offset:3072
	s_add_u32 s38, s72, 0xb0000
	s_addc_u32 s39, s73, 0
	s_mov_b32 m0, s52
	v_lshl_add_u64 v[216:217], s[38:39], 0, v[130:131]
	ds_read_b128 v[180:183], v253 offset:32768
	ds_read_b128 v[184:187], v253 offset:33792
	ds_read_b128 v[188:191], v253 offset:34816
	ds_read_b128 v[192:195], v253 offset:35840
	ds_read_b128 v[196:199], v253 offset:36864
	ds_read_b128 v[200:203], v253 offset:37888
	ds_read_b128 v[204:207], v253 offset:38912
	ds_read_b128 v[208:211], v253 offset:39936
	global_load_lds_dwordx4 v[216:217], off
	s_mov_b32 m0, s53
	v_lshl_add_u64 v[216:217], s[38:39], 0, v[132:133]
	global_load_lds_dwordx4 v[216:217], off
	s_waitcnt vmcnt(8)
	s_waitcnt lgkmcnt(0)
	s_setprio 1
	s_barrier
	v_mfma_f32_16x16x32_bf16 v[126:129], v[140:143], v[180:183], v[126:129]
	v_mfma_f32_16x16x32_bf16 v[122:125], v[156:159], v[180:183], v[122:125]
	v_mfma_f32_16x16x32_bf16 v[110:113], v[140:143], v[188:191], v[110:113]
	v_mfma_f32_16x16x32_bf16 v[106:109], v[156:159], v[188:191], v[106:109]
	v_mfma_f32_16x16x32_bf16 v[94:97], v[140:143], v[196:199], v[94:97]
	v_mfma_f32_16x16x32_bf16 v[90:93], v[156:159], v[196:199], v[90:93]
	v_mfma_f32_16x16x32_bf16 v[78:81], v[140:143], v[204:207], v[78:81]
	v_mfma_f32_16x16x32_bf16 v[74:77], v[156:159], v[204:207], v[74:77]
	v_mfma_f32_16x16x32_bf16 v[126:129], v[144:147], v[184:187], v[126:129]
	v_mfma_f32_16x16x32_bf16 v[122:125], v[160:163], v[184:187], v[122:125]
	v_mfma_f32_16x16x32_bf16 v[110:113], v[144:147], v[192:195], v[110:113]
	v_mfma_f32_16x16x32_bf16 v[106:109], v[160:163], v[192:195], v[106:109]
	v_mfma_f32_16x16x32_bf16 v[94:97], v[144:147], v[200:203], v[94:97]
	v_mfma_f32_16x16x32_bf16 v[90:93], v[160:163], v[200:203], v[90:93]
	v_mfma_f32_16x16x32_bf16 v[78:81], v[144:147], v[208:211], v[78:81]
	v_mfma_f32_16x16x32_bf16 v[74:77], v[160:163], v[208:211], v[74:77]
	v_mfma_f32_16x16x32_bf16 v[118:121], v[164:167], v[180:183], v[118:121]
	v_mfma_f32_16x16x32_bf16 v[114:117], v[172:175], v[180:183], v[114:117]
	v_mfma_f32_16x16x32_bf16 v[102:105], v[164:167], v[188:191], v[102:105]
	v_mfma_f32_16x16x32_bf16 v[98:101], v[172:175], v[188:191], v[98:101]
	v_mfma_f32_16x16x32_bf16 v[86:89], v[164:167], v[196:199], v[86:89]
	v_mfma_f32_16x16x32_bf16 v[82:85], v[172:175], v[196:199], v[82:85]
	v_mfma_f32_16x16x32_bf16 v[70:73], v[164:167], v[204:207], v[70:73]
	v_mfma_f32_16x16x32_bf16 v[66:69], v[172:175], v[204:207], v[66:69]
	v_mfma_f32_16x16x32_bf16 v[118:121], v[168:171], v[184:187], v[118:121]
	v_mfma_f32_16x16x32_bf16 v[114:117], v[176:179], v[184:187], v[114:117]
	v_mfma_f32_16x16x32_bf16 v[102:105], v[168:171], v[192:195], v[102:105]
	v_mfma_f32_16x16x32_bf16 v[98:101], v[176:179], v[192:195], v[98:101]
	v_mfma_f32_16x16x32_bf16 v[86:89], v[168:171], v[200:203], v[86:89]
	v_mfma_f32_16x16x32_bf16 v[82:85], v[176:179], v[200:203], v[82:85]
	v_mfma_f32_16x16x32_bf16 v[70:73], v[168:171], v[208:211], v[70:73]
	v_mfma_f32_16x16x32_bf16 v[66:69], v[176:179], v[208:211], v[66:69]
	s_setprio 0
	s_barrier
	s_add_i32 s38, s78, s49
	v_lshl_add_u64 v[148:149], v[148:149], 0, s[70:71]
	s_mov_b32 m0, s38
	ds_read_b128 v[180:183], v253 offset:49152
	ds_read_b128 v[184:187], v253 offset:50176
	ds_read_b128 v[188:191], v253 offset:51200
	ds_read_b128 v[192:195], v253 offset:52224
	ds_read_b128 v[196:199], v253 offset:53248
	ds_read_b128 v[200:203], v253 offset:54272
	ds_read_b128 v[204:207], v253 offset:55296
	ds_read_b128 v[208:211], v253 offset:56320
	global_load_lds_dwordx4 v[148:149], off
	s_add_i32 m0, s38, 0x2000
	s_add_u32 s26, s26, 0xb0080
	v_lshl_add_u64 v[148:149], v[150:151], 0, s[70:71]
	s_addc_u32 s27, s27, 0
	s_add_i32 s38, s79, s49
	global_load_lds_dwordx4 v[148:149], off
	s_mov_b32 m0, s38
	v_lshl_add_u64 v[148:149], s[26:27], 0, v[0:1]
	global_load_lds_dwordx4 v[148:149], off
	s_add_i32 m0, s38, 0x2000
	v_lshl_add_u64 v[148:149], s[26:27], 0, v[134:135]
	global_load_lds_dwordx4 v[148:149], off
	s_mov_b32 m0, s74
	v_lshl_add_u64 v[148:149], v[212:213], 0, s[70:71]
	global_load_lds_dwordx4 v[148:149], off
	s_mov_b32 m0, s75
	v_lshl_add_u64 v[148:149], v[214:215], 0, s[70:71]
	global_load_lds_dwordx4 v[148:149], off
	s_waitcnt vmcnt(8)
	s_waitcnt lgkmcnt(0)
	s_setprio 1
	s_barrier
	v_mfma_f32_16x16x32_bf16 v[62:65], v[140:143], v[180:183], v[62:65]
	v_mfma_f32_16x16x32_bf16 v[58:61], v[156:159], v[180:183], v[58:61]
	v_mfma_f32_16x16x32_bf16 v[46:49], v[140:143], v[188:191], v[46:49]
	v_mfma_f32_16x16x32_bf16 v[42:45], v[156:159], v[188:191], v[42:45]
	v_mfma_f32_16x16x32_bf16 v[30:33], v[140:143], v[196:199], v[30:33]
	v_mfma_f32_16x16x32_bf16 v[26:29], v[156:159], v[196:199], v[26:29]
	v_mfma_f32_16x16x32_bf16 v[14:17], v[140:143], v[204:207], v[14:17]
	v_mfma_f32_16x16x32_bf16 v[10:13], v[156:159], v[204:207], v[10:13]
	v_mfma_f32_16x16x32_bf16 v[62:65], v[144:147], v[184:187], v[62:65]
	v_mfma_f32_16x16x32_bf16 v[58:61], v[160:163], v[184:187], v[58:61]
	v_mfma_f32_16x16x32_bf16 v[46:49], v[144:147], v[192:195], v[46:49]
	v_mfma_f32_16x16x32_bf16 v[42:45], v[160:163], v[192:195], v[42:45]
	v_mfma_f32_16x16x32_bf16 v[30:33], v[144:147], v[200:203], v[30:33]
	v_mfma_f32_16x16x32_bf16 v[26:29], v[160:163], v[200:203], v[26:29]
	v_mfma_f32_16x16x32_bf16 v[14:17], v[144:147], v[208:211], v[14:17]
	v_mfma_f32_16x16x32_bf16 v[10:13], v[160:163], v[208:211], v[10:13]
	v_mfma_f32_16x16x32_bf16 v[54:57], v[164:167], v[180:183], v[54:57]
	v_mfma_f32_16x16x32_bf16 v[50:53], v[172:175], v[180:183], v[50:53]
	v_mfma_f32_16x16x32_bf16 v[38:41], v[164:167], v[188:191], v[38:41]
	v_mfma_f32_16x16x32_bf16 v[34:37], v[172:175], v[188:191], v[34:37]
	v_mfma_f32_16x16x32_bf16 v[22:25], v[164:167], v[196:199], v[22:25]
	v_mfma_f32_16x16x32_bf16 v[18:21], v[172:175], v[196:199], v[18:21]
	v_mfma_f32_16x16x32_bf16 v[6:9], v[164:167], v[204:207], v[6:9]
	v_mfma_f32_16x16x32_bf16 v[2:5], v[172:175], v[204:207], v[2:5]
	v_mfma_f32_16x16x32_bf16 v[54:57], v[168:171], v[184:187], v[54:57]
	v_mfma_f32_16x16x32_bf16 v[50:53], v[176:179], v[184:187], v[50:53]
	v_mfma_f32_16x16x32_bf16 v[38:41], v[168:171], v[192:195], v[38:41]
	v_mfma_f32_16x16x32_bf16 v[34:37], v[176:179], v[192:195], v[34:37]
	v_mfma_f32_16x16x32_bf16 v[22:25], v[168:171], v[200:203], v[22:25]
	v_mfma_f32_16x16x32_bf16 v[18:21], v[176:179], v[200:203], v[18:21]
	v_mfma_f32_16x16x32_bf16 v[6:9], v[168:171], v[208:211], v[6:9]
	v_mfma_f32_16x16x32_bf16 v[2:5], v[176:179], v[208:211], v[2:5]
	s_setprio 0
	s_barrier
	s_add_u32 vcc_lo, vcc_lo, 0x100
	s_addc_u32 vcc_hi, vcc_hi, 0
	s_cmp_ge_u32 s9, s28
	s_mov_b64 s[38:39], s[60:61]
	s_mov_b32 s26, s9
	s_cbranch_scc0 .LBB0_1000
	s_and_b64 vcc, exec, s[22:23]
	s_cbranch_vccz .LBB0_1003

.LBB0_1054:
	s_add_i32 s96, s26, 2
	s_add_u32 s36, s24, 0x100
	s_addc_u32 s37, s25, 0
	s_add_i32 s9, 0, 0x10000
	s_cmp_eq_u32 s93, s26
	s_cselect_b32 s39, s15, s37
	s_cselect_b32 s38, s14, s36
	v_add_u32_e32 v148, s9, v177
	s_cselect_b32 s27, s23, s95
	s_cselect_b32 s26, s22, s94
	s_add_i32 s78, 0, 0x14000
	ds_read_b128 v[140:143], v148
	ds_read_b128 v[144:147], v148 offset:1024
	ds_read_b128 v[156:159], v148 offset:2048
	ds_read_b128 v[160:163], v148 offset:3072
	v_add_u32_e32 v148, s78, v177
	ds_read_b128 v[164:167], v148
	ds_read_b128 v[168:171], v148 offset:1024
	ds_read_b128 v[172:175], v148 offset:2048
	ds_read_b128 v[180:183], v148 offset:3072
	v_lshl_add_u64 v[148:149], s[24:25], 0, v[136:137]
	s_add_i32 m0, s29, 0xc000
	ds_read_b128 v[184:187], v179
	ds_read_b128 v[188:191], v179 offset:1024
	ds_read_b128 v[192:195], v179 offset:2048
	ds_read_b128 v[196:199], v179 offset:3072
	ds_read_b128 v[200:203], v179 offset:4096
	ds_read_b128 v[204:207], v179 offset:5120
	ds_read_b128 v[208:211], v179 offset:6144
	ds_read_b128 v[212:215], v179 offset:7168
	global_load_lds_dwordx4 v[148:149], off
	s_add_i32 m0, s29, 0xe000
	v_lshl_add_u64 v[148:149], s[24:25], 0, v[138:139]
	global_load_lds_dwordx4 v[148:149], off
	s_waitcnt vmcnt(8)
	s_waitcnt lgkmcnt(0)
	s_setprio 1
	s_barrier
	v_mfma_f32_16x16x32_bf16 v[126:129], v[140:143], v[184:187], v[126:129]
	v_mfma_f32_16x16x32_bf16 v[122:125], v[156:159], v[184:187], v[122:125]
	v_mfma_f32_16x16x32_bf16 v[110:113], v[140:143], v[192:195], v[110:113]
	v_mfma_f32_16x16x32_bf16 v[106:109], v[156:159], v[192:195], v[106:109]
	v_mfma_f32_16x16x32_bf16 v[94:97], v[140:143], v[200:203], v[94:97]
	v_mfma_f32_16x16x32_bf16 v[90:93], v[156:159], v[200:203], v[90:93]
	v_mfma_f32_16x16x32_bf16 v[78:81], v[140:143], v[208:211], v[78:81]
	v_mfma_f32_16x16x32_bf16 v[74:77], v[156:159], v[208:211], v[74:77]
	v_mfma_f32_16x16x32_bf16 v[126:129], v[144:147], v[188:191], v[126:129]
	v_mfma_f32_16x16x32_bf16 v[122:125], v[160:163], v[188:191], v[122:125]
	v_mfma_f32_16x16x32_bf16 v[110:113], v[144:147], v[196:199], v[110:113]
	v_mfma_f32_16x16x32_bf16 v[106:109], v[160:163], v[196:199], v[106:109]
	v_mfma_f32_16x16x32_bf16 v[94:97], v[144:147], v[204:207], v[94:97]
	v_mfma_f32_16x16x32_bf16 v[90:93], v[160:163], v[204:207], v[90:93]
	v_mfma_f32_16x16x32_bf16 v[78:81], v[144:147], v[212:215], v[78:81]
	v_mfma_f32_16x16x32_bf16 v[74:77], v[160:163], v[212:215], v[74:77]
	v_mfma_f32_16x16x32_bf16 v[118:121], v[164:167], v[184:187], v[118:121]
	v_mfma_f32_16x16x32_bf16 v[114:117], v[172:175], v[184:187], v[114:117]
	v_mfma_f32_16x16x32_bf16 v[102:105], v[164:167], v[192:195], v[102:105]
	v_mfma_f32_16x16x32_bf16 v[98:101], v[172:175], v[192:195], v[98:101]
	v_mfma_f32_16x16x32_bf16 v[86:89], v[164:167], v[200:203], v[86:89]
	v_mfma_f32_16x16x32_bf16 v[82:85], v[172:175], v[200:203], v[82:85]
	v_mfma_f32_16x16x32_bf16 v[70:73], v[164:167], v[208:211], v[70:73]
	v_mfma_f32_16x16x32_bf16 v[66:69], v[172:175], v[208:211], v[66:69]
	v_mfma_f32_16x16x32_bf16 v[118:121], v[168:171], v[188:191], v[118:121]
	v_mfma_f32_16x16x32_bf16 v[114:117], v[180:183], v[188:191], v[114:117]
	v_mfma_f32_16x16x32_bf16 v[102:105], v[168:171], v[196:199], v[102:105]
	v_mfma_f32_16x16x32_bf16 v[98:101], v[180:183], v[196:199], v[98:101]
	v_mfma_f32_16x16x32_bf16 v[86:89], v[168:171], v[204:207], v[86:89]
	v_mfma_f32_16x16x32_bf16 v[82:85], v[180:183], v[204:207], v[82:85]
	v_mfma_f32_16x16x32_bf16 v[70:73], v[168:171], v[212:215], v[70:73]
	v_mfma_f32_16x16x32_bf16 v[66:69], v[180:183], v[212:215], v[66:69]
	s_setprio 0
	s_barrier
	s_add_i32 s9, s9, s28
	v_lshl_add_u64 v[148:149], s[26:27], 0, v[0:1]
	s_mov_b32 m0, s9
	ds_read_b128 v[184:187], v179 offset:16384
	ds_read_b128 v[188:191], v179 offset:17408
	ds_read_b128 v[192:195], v179 offset:18432
	ds_read_b128 v[196:199], v179 offset:19456
	ds_read_b128 v[200:203], v179 offset:20480
	ds_read_b128 v[204:207], v179 offset:21504
	ds_read_b128 v[208:211], v179 offset:22528
	ds_read_b128 v[212:215], v179 offset:23552
	global_load_lds_dwordx4 v[148:149], off
	s_add_i32 m0, s9, 0x2000
	s_add_u32 s24, s26, 0xb0000
	v_lshl_add_u64 v[150:151], s[26:27], 0, v[134:135]
	s_addc_u32 s25, s27, 0
	s_add_i32 s9, s78, s28
	global_load_lds_dwordx4 v[150:151], off
	v_lshl_add_u64 v[216:217], s[24:25], 0, v[0:1]
	s_mov_b32 m0, s9
	v_lshl_add_u64 v[218:219], s[38:39], 0, v[132:133]
	global_load_lds_dwordx4 v[216:217], off
	s_add_i32 m0, s9, 0x2000
	v_lshl_add_u64 v[216:217], s[24:25], 0, v[134:135]
	global_load_lds_dwordx4 v[216:217], off
	s_mov_b32 m0, s29
	v_lshl_add_u64 v[216:217], s[38:39], 0, v[130:131]
	global_load_lds_dwordx4 v[216:217], off
	s_mov_b32 m0, s49
	s_nop 0
	global_load_lds_dwordx4 v[218:219], off
	s_waitcnt vmcnt(8)
	s_waitcnt lgkmcnt(0)
	s_setprio 1
	s_barrier
	v_mfma_f32_16x16x32_bf16 v[62:65], v[140:143], v[184:187], v[62:65]
	v_mfma_f32_16x16x32_bf16 v[58:61], v[156:159], v[184:187], v[58:61]
	v_mfma_f32_16x16x32_bf16 v[46:49], v[140:143], v[192:195], v[46:49]
	v_mfma_f32_16x16x32_bf16 v[42:45], v[156:159], v[192:195], v[42:45]
	v_mfma_f32_16x16x32_bf16 v[30:33], v[140:143], v[200:203], v[30:33]
	v_mfma_f32_16x16x32_bf16 v[26:29], v[156:159], v[200:203], v[26:29]
	v_mfma_f32_16x16x32_bf16 v[14:17], v[140:143], v[208:211], v[14:17]
	v_mfma_f32_16x16x32_bf16 v[10:13], v[156:159], v[208:211], v[10:13]
	v_mfma_f32_16x16x32_bf16 v[62:65], v[144:147], v[188:191], v[62:65]
	v_mfma_f32_16x16x32_bf16 v[58:61], v[160:163], v[188:191], v[58:61]
	v_mfma_f32_16x16x32_bf16 v[46:49], v[144:147], v[196:199], v[46:49]
	v_mfma_f32_16x16x32_bf16 v[42:45], v[160:163], v[196:199], v[42:45]
	v_mfma_f32_16x16x32_bf16 v[30:33], v[144:147], v[204:207], v[30:33]
	v_mfma_f32_16x16x32_bf16 v[26:29], v[160:163], v[204:207], v[26:29]
	v_mfma_f32_16x16x32_bf16 v[14:17], v[144:147], v[212:215], v[14:17]
	v_mfma_f32_16x16x32_bf16 v[10:13], v[160:163], v[212:215], v[10:13]
	v_mfma_f32_16x16x32_bf16 v[54:57], v[164:167], v[184:187], v[54:57]
	v_mfma_f32_16x16x32_bf16 v[50:53], v[172:175], v[184:187], v[50:53]
	v_mfma_f32_16x16x32_bf16 v[38:41], v[164:167], v[192:195], v[38:41]
	v_mfma_f32_16x16x32_bf16 v[34:37], v[172:175], v[192:195], v[34:37]
	v_mfma_f32_16x16x32_bf16 v[22:25], v[164:167], v[200:203], v[22:25]
	v_mfma_f32_16x16x32_bf16 v[18:21], v[172:175], v[200:203], v[18:21]
	v_mfma_f32_16x16x32_bf16 v[6:9], v[164:167], v[208:211], v[6:9]
	v_mfma_f32_16x16x32_bf16 v[2:5], v[172:175], v[208:211], v[2:5]
	v_mfma_f32_16x16x32_bf16 v[54:57], v[168:171], v[188:191], v[54:57]
	v_mfma_f32_16x16x32_bf16 v[50:53], v[180:183], v[188:191], v[50:53]
	v_mfma_f32_16x16x32_bf16 v[38:41], v[168:171], v[196:199], v[38:41]
	v_mfma_f32_16x16x32_bf16 v[34:37], v[180:183], v[196:199], v[34:37]
	v_mfma_f32_16x16x32_bf16 v[22:25], v[168:171], v[204:207], v[22:25]
	v_mfma_f32_16x16x32_bf16 v[18:21], v[180:183], v[204:207], v[18:21]
	v_mfma_f32_16x16x32_bf16 v[6:9], v[168:171], v[212:215], v[6:9]
	v_mfma_f32_16x16x32_bf16 v[2:5], v[180:183], v[212:215], v[2:5]
	s_setprio 0
	s_barrier
	s_add_i32 s9, 0, 0x18000
	s_add_i32 s78, 0, 0x1c000
	v_add_u32_e32 v160, s9, v177
	v_add_u32_e32 v180, s78, v177
	ds_read_b128 v[140:143], v160
	ds_read_b128 v[144:147], v160 offset:1024
	ds_read_b128 v[156:159], v160 offset:2048
	ds_read_b128 v[160:163], v160 offset:3072
	ds_read_b128 v[164:167], v180
	ds_read_b128 v[168:171], v180 offset:1024
	ds_read_b128 v[172:175], v180 offset:2048
	ds_read_b128 v[180:183], v180 offset:3072
	s_add_u32 s24, s38, 0xb0000
	s_addc_u32 s25, s39, 0
	s_mov_b32 m0, s50
	v_lshl_add_u64 v[220:221], s[24:25], 0, v[130:131]
	ds_read_b128 v[184:187], v179 offset:32768
	ds_read_b128 v[188:191], v179 offset:33792
	ds_read_b128 v[192:195], v179 offset:34816
	ds_read_b128 v[196:199], v179 offset:35840
	ds_read_b128 v[200:203], v179 offset:36864
	ds_read_b128 v[204:207], v179 offset:37888
	ds_read_b128 v[208:211], v179 offset:38912
	ds_read_b128 v[212:215], v179 offset:39936
	global_load_lds_dwordx4 v[220:221], off
	s_mov_b32 m0, s51
	v_lshl_add_u64 v[220:221], s[24:25], 0, v[132:133]
	global_load_lds_dwordx4 v[220:221], off
	s_waitcnt vmcnt(8)
	s_waitcnt lgkmcnt(0)
	s_setprio 1
	s_barrier
	v_mfma_f32_16x16x32_bf16 v[126:129], v[140:143], v[184:187], v[126:129]
	v_mfma_f32_16x16x32_bf16 v[122:125], v[156:159], v[184:187], v[122:125]
	v_mfma_f32_16x16x32_bf16 v[110:113], v[140:143], v[192:195], v[110:113]
	v_mfma_f32_16x16x32_bf16 v[106:109], v[156:159], v[192:195], v[106:109]
	v_mfma_f32_16x16x32_bf16 v[94:97], v[140:143], v[200:203], v[94:97]
	v_mfma_f32_16x16x32_bf16 v[90:93], v[156:159], v[200:203], v[90:93]
	v_mfma_f32_16x16x32_bf16 v[78:81], v[140:143], v[208:211], v[78:81]
	v_mfma_f32_16x16x32_bf16 v[74:77], v[156:159], v[208:211], v[74:77]
	v_mfma_f32_16x16x32_bf16 v[126:129], v[144:147], v[188:191], v[126:129]
	v_mfma_f32_16x16x32_bf16 v[122:125], v[160:163], v[188:191], v[122:125]
	v_mfma_f32_16x16x32_bf16 v[110:113], v[144:147], v[196:199], v[110:113]
	v_mfma_f32_16x16x32_bf16 v[106:109], v[160:163], v[196:199], v[106:109]
	v_mfma_f32_16x16x32_bf16 v[94:97], v[144:147], v[204:207], v[94:97]
	v_mfma_f32_16x16x32_bf16 v[90:93], v[160:163], v[204:207], v[90:93]
	v_mfma_f32_16x16x32_bf16 v[78:81], v[144:147], v[212:215], v[78:81]
	v_mfma_f32_16x16x32_bf16 v[74:77], v[160:163], v[212:215], v[74:77]
	v_mfma_f32_16x16x32_bf16 v[118:121], v[164:167], v[184:187], v[118:121]
	v_mfma_f32_16x16x32_bf16 v[114:117], v[172:175], v[184:187], v[114:117]
	v_mfma_f32_16x16x32_bf16 v[102:105], v[164:167], v[192:195], v[102:105]
	v_mfma_f32_16x16x32_bf16 v[98:101], v[172:175], v[192:195], v[98:101]
	v_mfma_f32_16x16x32_bf16 v[86:89], v[164:167], v[200:203], v[86:89]
	v_mfma_f32_16x16x32_bf16 v[82:85], v[172:175], v[200:203], v[82:85]
	v_mfma_f32_16x16x32_bf16 v[70:73], v[164:167], v[208:211], v[70:73]
	v_mfma_f32_16x16x32_bf16 v[66:69], v[172:175], v[208:211], v[66:69]
	v_mfma_f32_16x16x32_bf16 v[118:121], v[168:171], v[188:191], v[118:121]
	v_mfma_f32_16x16x32_bf16 v[114:117], v[180:183], v[188:191], v[114:117]
	v_mfma_f32_16x16x32_bf16 v[102:105], v[168:171], v[196:199], v[102:105]
	v_mfma_f32_16x16x32_bf16 v[98:101], v[180:183], v[196:199], v[98:101]
	v_mfma_f32_16x16x32_bf16 v[86:89], v[168:171], v[204:207], v[86:89]
	v_mfma_f32_16x16x32_bf16 v[82:85], v[180:183], v[204:207], v[82:85]
	v_mfma_f32_16x16x32_bf16 v[70:73], v[168:171], v[212:215], v[70:73]
	v_mfma_f32_16x16x32_bf16 v[66:69], v[180:183], v[212:215], v[66:69]
	s_setprio 0
	s_barrier
	s_add_i32 s9, s9, s28
	v_lshl_add_u64 v[148:149], v[148:149], 0, s[70:71]
	s_mov_b32 m0, s9
	ds_read_b128 v[184:187], v179 offset:49152
	ds_read_b128 v[188:191], v179 offset:50176
	ds_read_b128 v[192:195], v179 offset:51200
	ds_read_b128 v[196:199], v179 offset:52224
	ds_read_b128 v[200:203], v179 offset:53248
	ds_read_b128 v[204:207], v179 offset:54272
	ds_read_b128 v[208:211], v179 offset:55296
	ds_read_b128 v[212:215], v179 offset:56320
	global_load_lds_dwordx4 v[148:149], off
	s_add_i32 m0, s9, 0x2000
	s_add_u32 s24, s26, 0xb0080
	v_lshl_add_u64 v[148:149], v[150:151], 0, s[70:71]
	s_addc_u32 s25, s27, 0
	s_add_i32 s9, s78, s28
	global_load_lds_dwordx4 v[148:149], off
	s_mov_b32 m0, s9
	v_lshl_add_u64 v[148:149], s[24:25], 0, v[0:1]
	global_load_lds_dwordx4 v[148:149], off
	s_add_i32 m0, s9, 0x2000
	v_lshl_add_u64 v[148:149], s[24:25], 0, v[134:135]
	global_load_lds_dwordx4 v[148:149], off
	s_mov_b32 m0, s52
	v_lshl_add_u64 v[148:149], v[216:217], 0, s[70:71]
	global_load_lds_dwordx4 v[148:149], off
	s_mov_b32 m0, s53
	v_lshl_add_u64 v[148:149], v[218:219], 0, s[70:71]
	global_load_lds_dwordx4 v[148:149], off
	s_waitcnt vmcnt(8)
	s_waitcnt lgkmcnt(0)
	s_setprio 1
	s_barrier
	v_mfma_f32_16x16x32_bf16 v[62:65], v[140:143], v[184:187], v[62:65]
	v_mfma_f32_16x16x32_bf16 v[58:61], v[156:159], v[184:187], v[58:61]
	v_mfma_f32_16x16x32_bf16 v[46:49], v[140:143], v[192:195], v[46:49]
	v_mfma_f32_16x16x32_bf16 v[42:45], v[156:159], v[192:195], v[42:45]
	v_mfma_f32_16x16x32_bf16 v[30:33], v[140:143], v[200:203], v[30:33]
	v_mfma_f32_16x16x32_bf16 v[26:29], v[156:159], v[200:203], v[26:29]
	v_mfma_f32_16x16x32_bf16 v[14:17], v[140:143], v[208:211], v[14:17]
	v_mfma_f32_16x16x32_bf16 v[10:13], v[156:159], v[208:211], v[10:13]
	v_mfma_f32_16x16x32_bf16 v[62:65], v[144:147], v[188:191], v[62:65]
	v_mfma_f32_16x16x32_bf16 v[58:61], v[160:163], v[188:191], v[58:61]
	v_mfma_f32_16x16x32_bf16 v[46:49], v[144:147], v[196:199], v[46:49]
	v_mfma_f32_16x16x32_bf16 v[42:45], v[160:163], v[196:199], v[42:45]
	v_mfma_f32_16x16x32_bf16 v[30:33], v[144:147], v[204:207], v[30:33]
	v_mfma_f32_16x16x32_bf16 v[26:29], v[160:163], v[204:207], v[26:29]
	v_mfma_f32_16x16x32_bf16 v[14:17], v[144:147], v[212:215], v[14:17]
	v_mfma_f32_16x16x32_bf16 v[10:13], v[160:163], v[212:215], v[10:13]
	v_mfma_f32_16x16x32_bf16 v[54:57], v[164:167], v[184:187], v[54:57]
	v_mfma_f32_16x16x32_bf16 v[50:53], v[172:175], v[184:187], v[50:53]
	v_mfma_f32_16x16x32_bf16 v[38:41], v[164:167], v[192:195], v[38:41]
	v_mfma_f32_16x16x32_bf16 v[34:37], v[172:175], v[192:195], v[34:37]
	v_mfma_f32_16x16x32_bf16 v[22:25], v[164:167], v[200:203], v[22:25]
	v_mfma_f32_16x16x32_bf16 v[18:21], v[172:175], v[200:203], v[18:21]
	v_mfma_f32_16x16x32_bf16 v[6:9], v[164:167], v[208:211], v[6:9]
	v_mfma_f32_16x16x32_bf16 v[2:5], v[172:175], v[208:211], v[2:5]
	v_mfma_f32_16x16x32_bf16 v[54:57], v[168:171], v[188:191], v[54:57]
	v_mfma_f32_16x16x32_bf16 v[50:53], v[180:183], v[188:191], v[50:53]
	v_mfma_f32_16x16x32_bf16 v[38:41], v[168:171], v[196:199], v[38:41]
	v_mfma_f32_16x16x32_bf16 v[34:37], v[180:183], v[196:199], v[34:37]
	v_mfma_f32_16x16x32_bf16 v[22:25], v[168:171], v[204:207], v[22:25]
	v_mfma_f32_16x16x32_bf16 v[18:21], v[180:183], v[204:207], v[18:21]
	v_mfma_f32_16x16x32_bf16 v[6:9], v[168:171], v[212:215], v[6:9]
	v_mfma_f32_16x16x32_bf16 v[2:5], v[180:183], v[212:215], v[2:5]
	s_setprio 0
	s_barrier
	s_add_u32 s94, s94, 0x100
	s_addc_u32 s95, s95, 0
	s_cmp_ge_u32 s96, s92
	s_mov_b64 s[24:25], s[36:37]
	s_mov_b32 s26, s96
	s_cbranch_scc0 .LBB0_1054
	s_and_b64 vcc, exec, s[12:13]
	s_cbranch_vccz .LBB0_1057
